# final norm reads the rows the last PG round wrote first (chunk bit swap) and the PG h3 stores drop nt so they can stay in the infinity cache
# speedup vs baseline: 1.0021x; 1.0021x over previous
; __global__ void __launch_bounds__(512, 2) mega(Params P0) {
;     ...
;         else if (ph == 11) { const float* r3 = (const float*)(ws + WS_RSS3); const float* fw = P.in[23]; const f32x4* h3 = (const f32x4*)(ws + WS_H1);
;             const int nchunk = NTOK * DM / 4 / 1024; const int wv = bid * 8 + (tid >> 6), lane = tid & 63;
;             for (int ck = wv; ck < nchunk; ck += G * 8) { f32x4 v[16];
; #pragma unroll
;                 for (int j = 0; j < 16; ++j) v[j] = __builtin_nontemporal_load(h3 + (ck * 16 + j) * 64 + lane);
; #pragma unroll
;                 for (int j = 0; j < 16; ++j) { const int i = (ck * 16 + j) * 64 + lane; const int row = i >> 8, c4 = i & 255; const float rstd = rsqrtf(r3[row] * (1.0f / DM) + 1e-6f);
;                     __builtin_nontemporal_store(v[j] * rstd * *(const f32x4*)(fw + 4 * c4), (f32x4*)P.out + i); } } }
.LBB0_725:
	v_add_u32_e32 v102, 0xfffffc40, v70
	v_lshrrev_b32_e32 v103, 3, v102
	v_lshlrev_b32_e32 v104, 3, v102
	v_and_b32_e32 v103, 0x80000, v103
	v_and_b32_e32 v104, 0x400000, v104
	v_and_b32_e32 v102, 0xffb7ffff, v102
	v_or3_b32 v102, v102, v103, v104
	v_xor_b32_e32 v102, 0x80000, v102
	v_ashrrev_i32_e32 v103, 31, v102
	v_ashrrev_i32_e32 v104, 8, v102
	v_ashrrev_i32_e32 v105, 31, v104
	v_lshl_add_u64 v[104:105], v[104:105], 2, s[4:5]
	global_load_dwordx4 v[76:79], v[104:105], off
	v_lshl_add_u64 v[88:89], v[102:103], 4, v[66:67]
	global_load_dwordx4 v[62:65], v[88:89], off nt
	global_load_dwordx4 v[58:61], v[88:89], off offset:1024 nt
	global_load_dwordx4 v[54:57], v[88:89], off offset:2048 nt
	global_load_dwordx4 v[50:53], v[88:89], off offset:3072 nt
	v_add_u32_e32 v90, 0x100, v102
	v_ashrrev_i32_e32 v91, 31, v90
	v_lshl_add_u64 v[90:91], v[90:91], 4, v[66:67]
	global_load_dwordx4 v[46:49], v[90:91], off nt
	global_load_dwordx4 v[42:45], v[90:91], off offset:1024 nt
	global_load_dwordx4 v[38:41], v[90:91], off offset:2048 nt
	global_load_dwordx4 v[34:37], v[90:91], off offset:3072 nt
	v_add_u32_e32 v92, 0x200, v102
	v_ashrrev_i32_e32 v93, 31, v92
	v_lshl_add_u64 v[92:93], v[92:93], 4, v[66:67]
	global_load_dwordx4 v[30:33], v[92:93], off nt
	global_load_dwordx4 v[26:29], v[92:93], off offset:1024 nt
	global_load_dwordx4 v[22:25], v[92:93], off offset:2048 nt
	global_load_dwordx4 v[18:21], v[92:93], off offset:3072 nt
	v_add_u32_e32 v94, 0x300, v102
	v_ashrrev_i32_e32 v95, 31, v94
	v_lshl_add_u64 v[94:95], v[94:95], 4, v[66:67]
	global_load_dwordx4 v[14:17], v[94:95], off nt
	global_load_dwordx4 v[10:13], v[94:95], off offset:1024 nt
	global_load_dwordx4 v[6:9], v[94:95], off offset:2048 nt
	global_load_dwordx4 v[2:5], v[94:95], off offset:3072 nt
	v_add_u32_e32 v100, s0, v100
	s_movk_i32 s10, 0x1fff
	v_add_u32_e32 v72, v0, v102
	v_ashrrev_i32_e32 v73, 31, v72
	v_lshl_add_u64 v[72:73], v[72:73], 4, s[20:21]
	v_add_u32_e32 v74, v0, v102
	v_add_u32_e32 v74, 0x100, v74
	v_ashrrev_i32_e32 v75, 31, v74
	v_lshl_add_u64 v[74:75], v[74:75], 4, s[20:21]
	v_add_u32_e32 v96, v0, v102
	v_add_u32_e32 v96, 0x200, v96
	v_ashrrev_i32_e32 v97, 31, v96
	v_lshl_add_u64 v[96:97], v[96:97], 4, s[20:21]
	v_add_u32_e32 v98, v0, v102
	v_add_u32_e32 v98, 0x300, v98
	v_ashrrev_i32_e32 v99, 31, v98
	v_lshl_add_u64 v[98:99], v[98:99], 4, s[20:21]
	s_waitcnt vmcnt(16)
	v_fmamk_f32 v80, v76, 0x3a800000, v210
	v_fmamk_f32 v82, v77, 0x3a800000, v210
	v_fmamk_f32 v84, v78, 0x3a800000, v210
	v_fmamk_f32 v86, v79, 0x3a800000, v210
	v_cmp_gt_f32_e64 s[40:41], s30, v80
	v_mul_f32_e32 v81, 0x4b800000, v80
	v_cmp_gt_f32_e64 s[42:43], s30, v82
	v_mul_f32_e32 v83, 0x4b800000, v82
	v_cmp_gt_f32_e64 s[44:45], s30, v84
	v_mul_f32_e32 v85, 0x4b800000, v84
	v_cmp_gt_f32_e64 s[46:47], s30, v86
	v_mul_f32_e32 v87, 0x4b800000, v86
	v_cndmask_b32_e64 v80, v80, v81, s[40:41]
	v_cndmask_b32_e64 v82, v82, v83, s[42:43]
	v_cndmask_b32_e64 v84, v84, v85, s[44:45]
	v_cndmask_b32_e64 v86, v86, v87, s[46:47]
	v_rsq_f32_e32 v80, v80
	v_rsq_f32_e32 v82, v82
	v_rsq_f32_e32 v84, v84
	v_rsq_f32_e32 v86, v86
	v_mul_f32_e32 v81, 0x45800000, v80
	v_mul_f32_e32 v83, 0x45800000, v82
	v_mul_f32_e32 v85, 0x45800000, v84
	v_mul_f32_e32 v87, 0x45800000, v86
	v_cndmask_b32_e64 v80, v80, v81, s[40:41]
	v_cndmask_b32_e64 v82, v82, v83, s[42:43]
	v_cndmask_b32_e64 v84, v84, v85, s[44:45]
	v_cndmask_b32_e64 v86, v86, v87, s[46:47]
	s_waitcnt vmcnt(15)
	v_pk_mul_f32 v[62:63], v[62:63], v[80:81] op_sel_hi:[1,0]
	v_pk_mul_f32 v[64:65], v[64:65], v[80:81] op_sel_hi:[1,0]
	v_pk_mul_f32 v[62:63], v[108:109], v[62:63]
	v_pk_mul_f32 v[64:65], v[110:111], v[64:65]
	s_waitcnt vmcnt(14)
	v_pk_mul_f32 v[58:59], v[58:59], v[80:81] op_sel_hi:[1,0]
	v_pk_mul_f32 v[60:61], v[60:61], v[80:81] op_sel_hi:[1,0]
	v_pk_mul_f32 v[58:59], v[112:113], v[58:59]
	v_pk_mul_f32 v[60:61], v[114:115], v[60:61]
	s_waitcnt vmcnt(13)
	v_pk_mul_f32 v[54:55], v[54:55], v[80:81] op_sel_hi:[1,0]
	v_pk_mul_f32 v[56:57], v[56:57], v[80:81] op_sel_hi:[1,0]
	v_pk_mul_f32 v[54:55], v[116:117], v[54:55]
	v_pk_mul_f32 v[56:57], v[118:119], v[56:57]
	s_waitcnt vmcnt(12)
; __global__ void __launch_bounds__(512, 2) mega(Params P0) {
;     ...
; #pragma unroll
;                 for (int j = 0; j < 16; ++j) { const int i = (ck * 16 + j) * 64 + lane; const int row = i >> 8, c4 = i & 255; const float rstd = rsqrtf(r3[row] * (1.0f / DM) + 1e-6f);
;                     __builtin_nontemporal_store(v[j] * rstd * *(const f32x4*)(fw + 4 * c4), (f32x4*)P.out + i); } } }
	v_pk_mul_f32 v[50:51], v[50:51], v[80:81] op_sel_hi:[1,0]
	v_pk_mul_f32 v[52:53], v[52:53], v[80:81] op_sel_hi:[1,0]
	v_pk_mul_f32 v[50:51], v[120:121], v[50:51]
	v_pk_mul_f32 v[52:53], v[122:123], v[52:53]
	global_store_dwordx4 v[72:73], v[62:65], off nt
	global_store_dwordx4 v[72:73], v[58:61], off offset:1024 nt
	global_store_dwordx4 v[72:73], v[54:57], off offset:2048 nt
	global_store_dwordx4 v[72:73], v[50:53], off offset:3072 nt
	s_waitcnt vmcnt(15)
	v_pk_mul_f32 v[46:47], v[46:47], v[82:83] op_sel_hi:[1,0]
	v_pk_mul_f32 v[48:49], v[48:49], v[82:83] op_sel_hi:[1,0]
	v_pk_mul_f32 v[46:47], v[108:109], v[46:47]
	v_pk_mul_f32 v[48:49], v[110:111], v[48:49]
	s_waitcnt vmcnt(14)
	v_pk_mul_f32 v[42:43], v[42:43], v[82:83] op_sel_hi:[1,0]
	v_pk_mul_f32 v[44:45], v[44:45], v[82:83] op_sel_hi:[1,0]
	v_pk_mul_f32 v[42:43], v[112:113], v[42:43]
	v_pk_mul_f32 v[44:45], v[114:115], v[44:45]
	s_waitcnt vmcnt(13)
	v_pk_mul_f32 v[38:39], v[38:39], v[82:83] op_sel_hi:[1,0]
	v_pk_mul_f32 v[40:41], v[40:41], v[82:83] op_sel_hi:[1,0]
	v_pk_mul_f32 v[38:39], v[116:117], v[38:39]
	v_pk_mul_f32 v[40:41], v[118:119], v[40:41]
	s_waitcnt vmcnt(12)
	v_pk_mul_f32 v[34:35], v[34:35], v[82:83] op_sel_hi:[1,0]
	v_pk_mul_f32 v[36:37], v[36:37], v[82:83] op_sel_hi:[1,0]
	v_pk_mul_f32 v[34:35], v[120:121], v[34:35]
	v_pk_mul_f32 v[36:37], v[122:123], v[36:37]
	global_store_dwordx4 v[74:75], v[46:49], off nt
	global_store_dwordx4 v[74:75], v[42:45], off offset:1024 nt
	global_store_dwordx4 v[74:75], v[38:41], off offset:2048 nt
	global_store_dwordx4 v[74:75], v[34:37], off offset:3072 nt
	s_waitcnt vmcnt(15)
	v_pk_mul_f32 v[30:31], v[30:31], v[84:85] op_sel_hi:[1,0]
	v_pk_mul_f32 v[32:33], v[32:33], v[84:85] op_sel_hi:[1,0]
	v_pk_mul_f32 v[30:31], v[108:109], v[30:31]
	v_pk_mul_f32 v[32:33], v[110:111], v[32:33]
	s_waitcnt vmcnt(14)
	v_pk_mul_f32 v[26:27], v[26:27], v[84:85] op_sel_hi:[1,0]
	v_pk_mul_f32 v[28:29], v[28:29], v[84:85] op_sel_hi:[1,0]
	v_pk_mul_f32 v[26:27], v[112:113], v[26:27]
	v_pk_mul_f32 v[28:29], v[114:115], v[28:29]
	s_waitcnt vmcnt(13)
	v_pk_mul_f32 v[22:23], v[22:23], v[84:85] op_sel_hi:[1,0]
	v_pk_mul_f32 v[24:25], v[24:25], v[84:85] op_sel_hi:[1,0]
	v_pk_mul_f32 v[22:23], v[116:117], v[22:23]
	v_pk_mul_f32 v[24:25], v[118:119], v[24:25]
	s_waitcnt vmcnt(12)
	v_pk_mul_f32 v[18:19], v[18:19], v[84:85] op_sel_hi:[1,0]
	v_pk_mul_f32 v[20:21], v[20:21], v[84:85] op_sel_hi:[1,0]
	v_pk_mul_f32 v[18:19], v[120:121], v[18:19]
	v_pk_mul_f32 v[20:21], v[122:123], v[20:21]
	global_store_dwordx4 v[96:97], v[30:33], off nt
	global_store_dwordx4 v[96:97], v[26:29], off offset:1024 nt
	global_store_dwordx4 v[96:97], v[22:25], off offset:2048 nt
	global_store_dwordx4 v[96:97], v[18:21], off offset:3072 nt
	s_waitcnt vmcnt(15)
	v_pk_mul_f32 v[14:15], v[14:15], v[86:87] op_sel_hi:[1,0]
	v_pk_mul_f32 v[16:17], v[16:17], v[86:87] op_sel_hi:[1,0]
	v_pk_mul_f32 v[14:15], v[108:109], v[14:15]
	v_pk_mul_f32 v[16:17], v[110:111], v[16:17]
	s_waitcnt vmcnt(14)
	v_pk_mul_f32 v[10:11], v[10:11], v[86:87] op_sel_hi:[1,0]
	v_pk_mul_f32 v[12:13], v[12:13], v[86:87] op_sel_hi:[1,0]
	v_pk_mul_f32 v[10:11], v[112:113], v[10:11]
	v_pk_mul_f32 v[12:13], v[114:115], v[12:13]
	s_waitcnt vmcnt(13)
	v_pk_mul_f32 v[6:7], v[6:7], v[86:87] op_sel_hi:[1,0]
	v_pk_mul_f32 v[8:9], v[8:9], v[86:87] op_sel_hi:[1,0]
	v_pk_mul_f32 v[6:7], v[116:117], v[6:7]
	v_pk_mul_f32 v[8:9], v[118:119], v[8:9]
	s_waitcnt vmcnt(12)
	v_pk_mul_f32 v[2:3], v[2:3], v[86:87] op_sel_hi:[1,0]
	v_pk_mul_f32 v[4:5], v[4:5], v[86:87] op_sel_hi:[1,0]
	v_pk_mul_f32 v[2:3], v[120:121], v[2:3]
	v_pk_mul_f32 v[4:5], v[122:123], v[4:5]
	global_store_dwordx4 v[98:99], v[14:17], off nt
	global_store_dwordx4 v[98:99], v[10:13], off offset:1024 nt
	global_store_dwordx4 v[98:99], v[6:9], off offset:2048 nt
	global_store_dwordx4 v[98:99], v[2:5], off offset:3072 nt
	v_add_u32_e32 v70, s9, v70
	v_add_u32_e32 v101, s8, v101
	v_cmp_lt_i32_e32 vcc, s10, v100
	s_nop 1
	s_or_b64 s[6:7], vcc, s[6:7]
	s_andn2_b64 exec, exec, s[6:7]
	s_cbranch_execnz .LBB0_725

; #define NTL(p) __builtin_nontemporal_load((const f32x4*)(p))
; __device__ __forceinline__ float bf_lo(unsigned w) { return __uint_as_float(w << 16); }
; __device__ __forceinline__ float bf_hi(unsigned w) { return __uint_as_float(w & 0xffff0000u); }
;     __device__ __forceinline__ void operator()(AccT& acc, const Unit& u, int wr, int wc, int fr, int fq) const {
;     ...
;         const int row0 = u.pm * 256 + wr * 64 + fr, col0 = u.pn * 256 + wc * 32 + 8 * fq;
;         f32x4 hv[2][4]; u32x4 pv[2][2]; float rs[2];
;         const bf16_t* ppbase = (u.L < 256 ? T0 : T1) + (size_t)(u.L & 255) * 65536 + (wr * 64 + fr) * 256 + wc * 32 + 8 * fq;
;         { const float* hr = H + (size_t)row0 * DM + col0; const bf16_t* pp = ppbase;
;           hv[0][0] = NTL(hr); hv[0][1] = NTL(hr + 4); hv[0][2] = NTL(hr + 128); hv[0][3] = NTL(hr + 132);
;           pv[0][0] = *(const u32x4*)pp; pv[0][1] = *(const u32x4*)(pp + 128); rs[0] = rss2[row0]; }
; #pragma unroll
;         for (int r = 0; r < 8; ++r) { const int ai = r >> 2, m = r & 3; const int row = row0 + ai * 128 + m * 16;
;             if (r < 7) { const int rn = row0 + ((r + 1) >> 2) * 128 + ((r + 1) & 3) * 16; const float* hn = H + (size_t)rn * DM + col0; const bf16_t* pn = ppbase + (((r + 1) >> 2) * 128 + ((r + 1) & 3) * 16) * 256;
;                 hv[(r + 1) & 1][0] = NTL(hn); hv[(r + 1) & 1][1] = NTL(hn + 4); hv[(r + 1) & 1][2] = NTL(hn + 128); hv[(r + 1) & 1][3] = NTL(hn + 132);
;                 pv[(r + 1) & 1][0] = *(const u32x4*)pn; pv[(r + 1) & 1][1] = *(const u32x4*)(pn + 128); rs[(r + 1) & 1] = rss2[rn]; }
;             float* hp = H + (size_t)row * DM + col0; float ss = 0.f; const float rstd = rsqrtf(rs[r & 1] * (1.0f / DM) + 1e-6f);
; #pragma unroll
;             for (int bj = 0; bj < 2; ++bj) { const u32x4 pw = pv[r & 1][bj];
;                 const f32x4 b0 = *(const f32x4*)(bias + col0 + bj * 128), b1 = *(const f32x4*)(bias + col0 + bj * 128 + 4);
;                 const f32x4 p0 = (f32x4){bf_lo(pw.x), bf_hi(pw.x), bf_lo(pw.y), bf_hi(pw.y)}, p1 = (f32x4){bf_lo(pw.z), bf_hi(pw.z), bf_lo(pw.w), bf_hi(pw.w)};
;                 f32x4 g0 = acc[ai][bj][m][0] * rstd + b0, g1 = acc[ai][bj][m][1] * rstd + b1;
; #pragma unroll
;                 for (int j = 0; j < 4; ++j) { g0[j] = sigmoidf_(g0[j]); g1[j] = sigmoidf_(g1[j]); }
.LBB0_781:
	v_mov_b32_e32 v130, v169
	v_mov_b32_e32 v145, v222
	v_add_u32_e32 v131, s79, v130
	v_lshl_add_u32 v186, s0, 8, v131
	s_lshl_b32 s0, s24, 8
	v_ashrrev_i32_e32 v187, 31, v186
	s_or_b32 s0, s0, s80
	v_lshl_add_u64 v[188:189], v[186:187], 2, s[34:35]
	s_cmpk_lt_i32 s26, 0x100
	global_load_dword v144, v[188:189], off
	s_cselect_b32 s3, s50, s53
	s_cselect_b32 s2, s51, s52
	s_lshl_b32 s4, s26, 17
	s_and_b32 s4, s4, 0x1fe0000
	s_add_u32 s2, s2, s4
	v_lshlrev_b32_e32 v132, 8, v131
	v_lshlrev_b32_e32 v130, 3, v145
	s_addc_u32 s3, s3, 0
	v_ashrrev_i32_e32 v133, 31, v132
	v_lshl_add_u64 v[132:133], v[132:133], 1, s[2:3]
	v_add_u32_e32 v192, s0, v130
	v_lshl_add_u64 v[132:133], v[132:133], 0, s[38:39]
	v_ashrrev_i32_e32 v131, 31, v130
	v_ashrrev_i32_e32 v193, 31, v192
	v_readlane_b32 s60, v255, 2
	v_lshl_add_u64 v[190:191], v[130:131], 1, v[132:133]
	v_lshlrev_b64 v[130:131], 2, v[192:193]
	v_readlane_b32 s72, v255, 14
	v_readlane_b32 s73, v255, 15
	global_load_dwordx4 v[138:141], v[190:191], off
	v_lshlrev_b64 v[132:133], 12, v[186:187]
	v_lshl_add_u64 v[184:185], s[72:73], 0, v[130:131]
	global_load_dwordx4 v[240:243], v[184:185], off
	global_load_dwordx4 v[244:247], v[184:185], off offset:16
	global_load_dwordx4 v[248:251], v[184:185], off offset:512
	global_load_dwordx4 v[232:235], v[184:185], off offset:528
	v_add_u32_e32 v198, 16, v186
	v_lshl_add_u64 v[132:133], s[22:23], 0, v[132:133]
	v_ashrrev_i32_e32 v199, 31, v198
	v_lshl_add_u64 v[142:143], v[132:133], 0, v[130:131]
	v_add_co_u32_e32 v132, vcc, s85, v190
	v_lshl_add_u64 v[134:135], v[198:199], 2, s[34:35]
	s_nop 0
	v_addc_co_u32_e32 v133, vcc, 0, v191, vcc
	global_load_dword v165, v[134:135], off
	global_load_dwordx4 v[170:173], v[142:143], off offset:16 nt
	global_load_dwordx4 v[194:197], v[142:143], off nt
	s_nop 0
	global_load_dwordx4 v[134:137], v[190:191], off offset:256
	global_load_dwordx4 v[158:161], v[132:133], off
	global_load_dwordx4 v[146:149], v[132:133], off offset:256
	v_readlane_b32 s61, v255, 3
	v_readlane_b32 s62, v255, 4
	v_readlane_b32 s63, v255, 5
	v_readlane_b32 s64, v255, 6
	v_readlane_b32 s65, v255, 7
	v_readlane_b32 s66, v255, 8
	v_readlane_b32 s67, v255, 9
	v_readlane_b32 s68, v255, 10
	v_readlane_b32 s69, v255, 11
	v_readlane_b32 s70, v255, 12
	v_readlane_b32 s71, v255, 13
	v_readlane_b32 s74, v255, 16
	v_readlane_b32 s75, v255, 17
	s_waitcnt vmcnt(11)
	v_fmamk_f32 v132, v144, 0x3a800000, v210
	v_mul_f32_e32 v133, 0x4b800000, v132
	v_cmp_gt_f32_e32 vcc, s30, v132
	s_waitcnt vmcnt(10)
	v_lshlrev_b32_e32 v166, 16, v140
	s_nop 0
	v_cndmask_b32_e32 v132, v132, v133, vcc
	v_rsq_f32_e32 v144, v132
	v_lshlrev_b32_e32 v132, 16, v138
	v_and_b32_e32 v133, 0xffff0000, v138
	v_lshlrev_b32_e32 v138, 16, v139
	v_mul_f32_e32 v164, 0x45800000, v144
	v_cndmask_b32_e32 v144, v144, v164, vcc
	s_waitcnt vmcnt(9)
	v_pk_fma_f32 v[124:125], v[124:125], v[144:145], v[242:243] op_sel_hi:[1,0,1]
	v_pk_fma_f32 v[122:123], v[122:123], v[144:145], v[240:241] op_sel_hi:[1,0,1]
	s_waitcnt vmcnt(8)
	v_pk_fma_f32 v[114:115], v[114:115], v[144:145], v[244:245] op_sel_hi:[1,0,1]
	v_mul_f32_e32 v122, 0xbfb8aa3b, v122
	v_mul_f32_e32 v123, 0xbfb8aa3b, v123
	v_mul_f32_e32 v151, 0xbfb8aa3b, v115
	v_mul_f32_e32 v115, 0xbfb8aa3b, v124
	v_mul_f32_e32 v150, 0xbfb8aa3b, v114
	v_exp_f32_e32 v114, v122
	v_exp_f32_e32 v124, v115
	v_exp_f32_e32 v115, v123
	v_mul_f32_e32 v125, 0xbfb8aa3b, v125
	v_exp_f32_e32 v125, v125
	v_exp_f32_e32 v122, v150
	v_pk_add_f32 v[114:115], v[114:115], 1.0 op_sel_hi:[1,0]
	v_pk_fma_f32 v[116:117], v[116:117], v[144:145], v[246:247] op_sel_hi:[1,0,1]
	v_pk_add_f32 v[124:125], v[124:125], 1.0 op_sel_hi:[1,0]
	v_div_scale_f32 v152, s[2:3], v114, v114, 1.0
	v_rcp_f32_e32 v155, v152
	v_exp_f32_e32 v123, v151
	v_fma_f32 v200, -v152, v155, 1.0
	v_div_scale_f32 v157, s[42:43], 1.0, v114, 1.0
	v_fmac_f32_e32 v155, v200, v155
	v_mul_f32_e32 v200, v157, v155
	v_fma_f32 v202, -v152, v200, v157
	v_fmac_f32_e32 v200, v202, v155
	v_fma_f32 v151, -v152, v200, v157
	s_mov_b64 vcc, s[42:43]
	v_rcp_f32_e32 v150, v115
	s_nop 0
	v_fma_f32 v164, -v115, v150, 1.0
	v_fma_f32 v115, v164, v150, v150
	v_div_fmas_f32 v150, v151, v155, v200
	v_div_fixup_f32 v114, v150, v114, 1.0
	v_rcp_f32_e32 v156, v125
	s_nop 0
	v_fma_f32 v201, -v125, v156, 1.0
	v_fma_f32 v125, v201, v156, v156
	v_pk_add_f32 v[122:123], v[122:123], 1.0 op_sel_hi:[1,0]
	v_rcp_f32_e32 v151, v124
	s_nop 0
	v_fma_f32 v153, -v124, v151, 1.0
	v_fma_f32 v124, v153, v151, v151
	v_mul_f32_e32 v116, 0xbfb8aa3b, v116
	v_mul_f32_e32 v117, 0xbfb8aa3b, v117
	v_exp_f32_e32 v116, v116
	v_exp_f32_e32 v117, v117
	v_rcp_f32_e32 v151, v123
	s_nop 0
	v_fma_f32 v154, -v123, v151, 1.0
	v_fma_f32 v123, v154, v151, v151
	v_pk_add_f32 v[116:117], v[116:117], 1.0 op_sel_hi:[1,0]
	v_rcp_f32_e32 v151, v122
	s_nop 0
	v_fma_f32 v153, -v122, v151, 1.0
	v_fma_f32 v122, v153, v151, v151
	v_and_b32_e32 v139, 0xffff0000, v139
	v_rcp_f32_e32 v154, v117
	s_nop 0
	v_fma_f32 v151, -v117, v154, 1.0
	v_fma_f32 v151, v151, v154, v154
	v_and_b32_e32 v167, 0xffff0000, v140
	v_lshlrev_b32_e32 v140, 16, v141
	v_and_b32_e32 v141, 0xffff0000, v141
	v_rcp_f32_e32 v154, v116
	s_nop 0
	v_fma_f32 v153, -v116, v154, 1.0
	v_fma_f32 v150, v153, v154, v154
	s_waitcnt vmcnt(3)
; #define NTS(v, p) __builtin_nontemporal_store((v), (f32x4*)(p))
; __device__ __forceinline__ float bf_lo(unsigned w) { return __uint_as_float(w << 16); }
; __device__ __forceinline__ float bf_hi(unsigned w) { return __uint_as_float(w & 0xffff0000u); }
; __device__ __forceinline__ float sigmoidf_(float x) { return 1.0f / (1.0f + __expf(-x)); }
;     __device__ __forceinline__ void operator()(AccT& acc, const Unit& u, int wr, int wc, int fr, int fq) const {
;     ...
;             float* hp = H + (size_t)row * DM + col0; float ss = 0.f; const float rstd = rsqrtf(rs[r & 1] * (1.0f / DM) + 1e-6f);
; #pragma unroll
;             for (int bj = 0; bj < 2; ++bj) { const u32x4 pw = pv[r & 1][bj];
;                 const f32x4 b0 = *(const f32x4*)(bias + col0 + bj * 128), b1 = *(const f32x4*)(bias + col0 + bj * 128 + 4);
;                 const f32x4 p0 = (f32x4){bf_lo(pw.x), bf_hi(pw.x), bf_lo(pw.y), bf_hi(pw.y)}, p1 = (f32x4){bf_lo(pw.z), bf_hi(pw.z), bf_lo(pw.w), bf_hi(pw.w)};
;                 f32x4 g0 = acc[ai][bj][m][0] * rstd + b0, g1 = acc[ai][bj][m][1] * rstd + b1;
; #pragma unroll
;                 for (int j = 0; j < 4; ++j) { g0[j] = sigmoidf_(g0[j]); g1[j] = sigmoidf_(g1[j]); }
;                 const f32x4 v0 = hv[r & 1][2 * bj] + p0 * g0, v1 = hv[r & 1][2 * bj + 1] + p1 * g1;
;                 NTS(v0, hp + bj * 128); NTS(v1, hp + bj * 128 + 4);
; #pragma unroll
;                 for (int j = 0; j < 4; ++j) ss += v0[j] * v0[j] + v1[j] * v1[j]; }
;             ss += __shfl_xor(ss, 16); ss += __shfl_xor(ss, 32);
;             if (fq == 0) unsafeAtomicAdd(rss3 + row, ss); __builtin_amdgcn_sched_barrier(0); }
	v_pk_fma_f32 v[116:117], v[124:125], v[138:139], v[196:197]
	v_pk_fma_f32 v[114:115], v[114:115], v[132:133], v[194:195]
	v_pk_fma_f32 v[124:125], v[150:151], v[140:141], v[172:173]
	v_pk_fma_f32 v[122:123], v[122:123], v[166:167], v[170:171]
	global_store_dwordx4 v[142:143], v[114:117], off
	global_store_dwordx4 v[142:143], v[122:125], off offset:16
	s_nop 0
	s_nop 0
	global_load_dwordx4 v[204:207], v[142:143], off offset:528 nt
	global_load_dwordx4 v[226:229], v[142:143], off offset:512 nt
	v_mul_f32_e32 v122, v122, v122
	v_fmac_f32_e32 v122, v114, v114
	v_mul_f32_e32 v114, v123, v123
	v_fmac_f32_e32 v114, v115, v115
	v_mul_f32_e32 v115, v124, v124
	v_add_f32_e32 v114, v122, v114
	v_fmac_f32_e32 v115, v116, v116
	v_add_f32_e32 v114, v115, v114
	v_mul_f32_e32 v115, v125, v125
	v_fmac_f32_e32 v115, v117, v117
	v_add_f32_e32 v166, v115, v114
	s_waitcnt vmcnt(6)
	v_lshlrev_b32_e32 v114, 16, v134
	v_and_b32_e32 v115, 0xffff0000, v134
	v_lshlrev_b32_e32 v116, 16, v135
	v_and_b32_e32 v117, 0xffff0000, v135
	v_and_b32_e32 v133, 64, v203
	v_xor_b32_e32 v132, 16, v203
	v_add_u32_e32 v164, 64, v133
	v_cmp_lt_i32_e32 vcc, v132, v164
	v_lshlrev_b32_e32 v122, 16, v136
	v_and_b32_e32 v123, 0xffff0000, v136
	v_cndmask_b32_e32 v132, v203, v132, vcc
	v_lshlrev_b32_e32 v124, 16, v137
	v_and_b32_e32 v125, 0xffff0000, v137
	v_lshlrev_b32_e32 v225, 2, v132
	v_lshlrev_b64 v[132:133], 12, v[198:199]
	v_lshl_add_u64 v[132:133], s[22:23], 0, v[132:133]
	v_lshl_add_u64 v[200:201], v[132:133], 0, v[130:131]
	global_load_dwordx4 v[150:153], v[200:201], off offset:16 nt
	global_load_dwordx4 v[154:157], v[200:201], off nt
	global_load_dwordx4 v[130:133], v[200:201], off offset:528 nt
	global_load_dwordx4 v[138:141], v[200:201], off offset:512 nt
	v_cmp_eq_u32_e64 s[42:43], 0, v145
	v_pk_fma_f32 v[110:111], v[110:111], v[144:145], v[248:249] op_sel_hi:[1,0,1]
	s_nop 0
	v_mul_f32_e32 v110, 0xbfb8aa3b, v110
	v_mul_f32_e32 v111, 0xbfb8aa3b, v111
	v_exp_f32_e32 v110, v110
	v_exp_f32_e32 v111, v111
	v_pk_fma_f32 v[112:113], v[112:113], v[144:145], v[250:251] op_sel_hi:[1,0,1]
	v_pk_fma_f32 v[108:109], v[108:109], v[144:145], v[234:235] op_sel_hi:[1,0,1]
	v_pk_fma_f32 v[106:107], v[106:107], v[144:145], v[232:233] op_sel_hi:[1,0,1]
	v_pk_add_f32 v[110:111], v[110:111], 1.0 op_sel_hi:[1,0]
	v_mul_f32_e32 v112, 0xbfb8aa3b, v112
	v_mul_f32_e32 v113, 0xbfb8aa3b, v113
	v_exp_f32_e32 v112, v112
	v_exp_f32_e32 v113, v113
	v_div_scale_f32 v136, s[2:3], v110, v110, 1.0
	v_rcp_f32_e32 v144, v136
	v_rcp_f32_e32 v134, v111
	s_nop 0
	v_fma_f32 v137, -v111, v134, 1.0
	v_fma_f32 v135, v137, v134, v134
	v_pk_add_f32 v[112:113], v[112:113], 1.0 op_sel_hi:[1,0]
	v_fma_f32 v111, -v136, v144, 1.0
	v_fmac_f32_e32 v144, v111, v144
	v_div_scale_f32 v111, vcc, 1.0, v110, 1.0
	v_mul_f32_e32 v134, v111, v144
	v_fma_f32 v137, -v136, v134, v111
	v_fmac_f32_e32 v134, v137, v144
	v_fma_f32 v111, -v136, v134, v111
	v_div_scale_f32 v136, s[2:3], v113, v113, 1.0
	v_rcp_f32_e32 v137, v136
	v_div_fmas_f32 v111, v111, v144, v134
	v_div_fixup_f32 v134, v111, v110, 1.0
	v_mul_f32_e32 v106, 0xbfb8aa3b, v106
	v_fma_f32 v110, -v136, v137, 1.0
	v_fmac_f32_e32 v137, v110, v137
	v_div_scale_f32 v110, vcc, 1.0, v113, 1.0
	v_mul_f32_e32 v111, v110, v137
	v_fma_f32 v144, -v136, v111, v110
	v_fmac_f32_e32 v111, v144, v137
	v_fma_f32 v110, -v136, v111, v110
	v_div_scale_f32 v136, s[2:3], v112, v112, 1.0
	v_rcp_f32_e32 v144, v136
	v_mul_f32_e32 v107, 0xbfb8aa3b, v107
	v_div_fmas_f32 v110, v110, v137, v111
	v_exp_f32_e32 v106, v106
	v_exp_f32_e32 v107, v107
	v_div_fixup_f32 v111, v110, v113, 1.0
	v_fma_f32 v110, -v136, v144, 1.0
	v_fmac_f32_e32 v144, v110, v144
	v_div_scale_f32 v110, vcc, 1.0, v112, 1.0
	v_mul_f32_e32 v113, v110, v144
	v_fma_f32 v137, -v136, v113, v110
	v_fmac_f32_e32 v113, v137, v144
	v_pk_add_f32 v[106:107], v[106:107], 1.0 op_sel_hi:[1,0]
	v_fma_f32 v110, -v136, v113, v110
	v_div_scale_f32 v136, s[2:3], v107, v107, 1.0
	v_rcp_f32_e32 v137, v136
	v_div_fmas_f32 v110, v110, v144, v113
	v_div_fixup_f32 v110, v110, v112, 1.0
	v_mul_f32_e32 v108, 0xbfb8aa3b, v108
	v_fma_f32 v112, -v136, v137, 1.0
	v_fmac_f32_e32 v137, v112, v137
	v_div_scale_f32 v112, vcc, 1.0, v107, 1.0
	v_mul_f32_e32 v113, v112, v137
	v_fma_f32 v144, -v136, v113, v112
	v_fmac_f32_e32 v113, v144, v137
	v_fma_f32 v112, -v136, v113, v112
	v_div_scale_f32 v136, s[2:3], v106, v106, 1.0
	v_rcp_f32_e32 v144, v136
	v_mul_f32_e32 v109, 0xbfb8aa3b, v109
	v_div_fmas_f32 v112, v112, v137, v113
	v_exp_f32_e32 v108, v108
	v_exp_f32_e32 v109, v109
	v_div_fixup_f32 v107, v112, v107, 1.0
	v_fma_f32 v112, -v136, v144, 1.0
	v_fmac_f32_e32 v144, v112, v144
	v_div_scale_f32 v112, vcc, 1.0, v106, 1.0
	v_mul_f32_e32 v113, v112, v144
	v_fma_f32 v137, -v136, v113, v112
	v_pk_add_f32 v[108:109], v[108:109], 1.0 op_sel_hi:[1,0]
	v_fmac_f32_e32 v113, v137, v144
	v_fma_f32 v112, -v136, v113, v112
	v_div_scale_f32 v136, s[2:3], v109, v109, 1.0
	v_rcp_f32_e32 v137, v136
	v_div_fmas_f32 v112, v112, v144, v113
	v_div_fixup_f32 v106, v112, v106, 1.0
	s_waitcnt vmcnt(4)
	v_pk_fma_f32 v[110:111], v[110:111], v[116:117], v[228:229]
	v_fma_f32 v112, -v136, v137, 1.0
	v_fmac_f32_e32 v137, v112, v137
	v_div_scale_f32 v112, vcc, 1.0, v109, 1.0
	v_mul_f32_e32 v113, v112, v137
	v_fma_f32 v144, -v136, v113, v112
	v_fmac_f32_e32 v113, v144, v137
	v_fma_f32 v112, -v136, v113, v112
	v_div_fmas_f32 v112, v112, v137, v113
	v_div_fixup_f32 v113, v112, v109, 1.0
	v_xor_b32_e32 v116, 32, v203
	v_rcp_f32_e32 v144, v108
	s_nop 0
	v_fma_f32 v136, -v108, v144, 1.0
	v_fma_f32 v112, v136, v144, v144
	v_pk_fma_f32 v[108:109], v[134:135], v[114:115], v[226:227]
	v_pk_fma_f32 v[114:115], v[112:113], v[124:125], v[206:207]
	v_pk_fma_f32 v[112:113], v[106:107], v[122:123], v[204:205]
	v_cmp_lt_i32_e32 vcc, v116, v164
	v_mul_f32_e32 v106, v112, v112
	v_fmac_f32_e32 v106, v108, v108
	v_mul_f32_e32 v107, v113, v113
	v_add_f32_e32 v106, v106, v166
	v_fmac_f32_e32 v107, v109, v109
	v_add_f32_e32 v106, v107, v106
	v_mul_f32_e32 v107, v114, v114
	v_fmac_f32_e32 v107, v110, v110
	v_add_f32_e32 v106, v107, v106
	v_mul_f32_e32 v107, v115, v115
	v_fmac_f32_e32 v107, v111, v111
	v_add_f32_e32 v106, v107, v106
	ds_bpermute_b32 v107, v225, v106
	v_cndmask_b32_e32 v116, v203, v116, vcc
	v_lshlrev_b32_e32 v226, 2, v116
	global_store_dwordx4 v[142:143], v[108:111], off offset:512
	global_store_dwordx4 v[142:143], v[112:115], off offset:528
	s_waitcnt lgkmcnt(0)
	v_add_f32_e32 v106, v106, v107
	ds_bpermute_b32 v107, v226, v106
	s_and_saveexec_b64 s[2:3], s[42:43]
	s_cbranch_execz .LBB0_783
	v_lshl_add_u64 v[108:109], v[186:187], 2, s[36:37]
	s_waitcnt lgkmcnt(0)
	v_add_f32_e32 v106, v106, v107
	global_atomic_add_f32 v[108:109], v106, off
; #define NTL(p) __builtin_nontemporal_load((const f32x4*)(p))
; #define NTS(v, p) __builtin_nontemporal_store((v), (f32x4*)(p))
; __device__ __forceinline__ float bf_lo(unsigned w) { return __uint_as_float(w << 16); }
; __device__ __forceinline__ float bf_hi(unsigned w) { return __uint_as_float(w & 0xffff0000u); }
; __device__ __forceinline__ float sigmoidf_(float x) { return 1.0f / (1.0f + __expf(-x)); }
;     __device__ __forceinline__ void operator()(AccT& acc, const Unit& u, int wr, int wc, int fr, int fq) const {
;     ...
;             if (r < 7) { const int rn = row0 + ((r + 1) >> 2) * 128 + ((r + 1) & 3) * 16; const float* hn = H + (size_t)rn * DM + col0; const bf16_t* pn = ppbase + (((r + 1) >> 2) * 128 + ((r + 1) & 3) * 16) * 256;
;                 hv[(r + 1) & 1][0] = NTL(hn); hv[(r + 1) & 1][1] = NTL(hn + 4); hv[(r + 1) & 1][2] = NTL(hn + 128); hv[(r + 1) & 1][3] = NTL(hn + 132);
;                 pv[(r + 1) & 1][0] = *(const u32x4*)pn; pv[(r + 1) & 1][1] = *(const u32x4*)(pn + 128); rs[(r + 1) & 1] = rss2[rn]; }
;             float* hp = H + (size_t)row * DM + col0; float ss = 0.f; const float rstd = rsqrtf(rs[r & 1] * (1.0f / DM) + 1e-6f);
; #pragma unroll
;             for (int bj = 0; bj < 2; ++bj) { const u32x4 pw = pv[r & 1][bj];
;                 const f32x4 b0 = *(const f32x4*)(bias + col0 + bj * 128), b1 = *(const f32x4*)(bias + col0 + bj * 128 + 4);
;                 const f32x4 p0 = (f32x4){bf_lo(pw.x), bf_hi(pw.x), bf_lo(pw.y), bf_hi(pw.y)}, p1 = (f32x4){bf_lo(pw.z), bf_hi(pw.z), bf_lo(pw.w), bf_hi(pw.w)};
;                 f32x4 g0 = acc[ai][bj][m][0] * rstd + b0, g1 = acc[ai][bj][m][1] * rstd + b1;
; #pragma unroll
;                 for (int j = 0; j < 4; ++j) { g0[j] = sigmoidf_(g0[j]); g1[j] = sigmoidf_(g1[j]); }
;                 const f32x4 v0 = hv[r & 1][2 * bj] + p0 * g0, v1 = hv[r & 1][2 * bj + 1] + p1 * g1;
;                 NTS(v0, hp + bj * 128); NTS(v1, hp + bj * 128 + 4);
; #pragma unroll
;                 for (int j = 0; j < 4; ++j) ss += v0[j] * v0[j] + v1[j] * v1[j]; }
.LBB0_783:
	s_or_b64 exec, exec, s[2:3]
	v_add_u32_e32 v194, 32, v186
	v_ashrrev_i32_e32 v195, 31, v194
	s_waitcnt lgkmcnt(0)
	v_lshlrev_b64 v[106:107], 12, v[194:195]
	v_lshl_add_u64 v[106:107], s[22:23], 0, v[106:107]
	v_add_co_u32_e32 v114, vcc, 0x4000, v190
	v_lshl_add_u64 v[196:197], v[192:193], 2, v[106:107]
	s_nop 0
	v_addc_co_u32_e32 v115, vcc, 0, v191, vcc
	global_load_dwordx4 v[122:125], v[196:197], off offset:16 nt
	global_load_dwordx4 v[134:137], v[196:197], off nt
	global_load_dwordx4 v[106:109], v[196:197], off offset:528 nt
	global_load_dwordx4 v[110:113], v[196:197], off offset:512 nt
	global_load_dwordx4 v[142:145], v[114:115], off
	s_nop 0
	global_load_dwordx4 v[114:117], v[114:115], off offset:256
	s_nop 0
	global_load_dword v164, v[188:189], off offset:128
	v_fmamk_f32 v165, v165, 0x3a800000, v210
	v_cmp_gt_f32_e32 vcc, s30, v165
	v_mul_f32_e32 v166, 0x4b800000, v165
	v_lshlrev_b32_e32 v204, 16, v158
	v_cndmask_b32_e32 v165, v165, v166, vcc
	v_rsq_f32_e32 v165, v165
	v_and_b32_e32 v205, 0xffff0000, v158
	v_lshlrev_b32_e32 v206, 16, v159
	v_and_b32_e32 v207, 0xffff0000, v159
	v_mul_f32_e32 v166, 0x45800000, v165
	v_cndmask_b32_e32 v202, v165, v166, vcc
	v_lshlrev_b32_e32 v158, 16, v160
	v_and_b32_e32 v159, 0xffff0000, v160
	v_lshlrev_b32_e32 v160, 16, v161
	v_and_b32_e32 v161, 0xffff0000, v161
	v_pk_fma_f32 v[118:119], v[118:119], v[202:203], v[244:245] op_sel_hi:[1,0,1]
	v_pk_fma_f32 v[126:127], v[126:127], v[202:203], v[240:241] op_sel_hi:[1,0,1]
	v_mul_f32_e32 v118, 0xbfb8aa3b, v118
	v_mul_f32_e32 v126, 0xbfb8aa3b, v126
	v_pk_fma_f32 v[120:121], v[120:121], v[202:203], v[246:247] op_sel_hi:[1,0,1]
	v_exp_f32_e32 v166, v126
	v_exp_f32_e32 v126, v118
	v_mul_f32_e32 v118, 0xbfb8aa3b, v127
	v_pk_fma_f32 v[128:129], v[128:129], v[202:203], v[242:243] op_sel_hi:[1,0,1]
	v_exp_f32_e32 v167, v118
	v_mul_f32_e32 v118, 0xbfb8aa3b, v119
	v_mul_f32_e32 v119, 0xbfb8aa3b, v120
	v_exp_f32_e32 v127, v118
	v_mul_f32_e32 v118, 0xbfb8aa3b, v128
	v_exp_f32_e32 v120, v119
	v_mul_f32_e32 v119, 0xbfb8aa3b, v129
	v_exp_f32_e32 v118, v118
	v_exp_f32_e32 v119, v119
	v_pk_add_f32 v[126:127], v[126:127], 1.0 op_sel_hi:[1,0]
	v_mul_f32_e32 v121, 0xbfb8aa3b, v121
	v_exp_f32_e32 v121, v121
	v_pk_add_f32 v[128:129], v[118:119], 1.0 op_sel_hi:[1,0]
	v_pk_add_f32 v[118:119], v[166:167], 1.0 op_sel_hi:[1,0]
	v_pk_add_f32 v[120:121], v[120:121], 1.0 op_sel_hi:[1,0]
	s_nop 0
	v_rcp_f32_e32 v165, v119
	s_nop 0
	v_fma_f32 v170, -v119, v165, 1.0
	v_fma_f32 v119, v170, v165, v165
	s_nop 0
	v_rcp_f32_e32 v165, v118
	s_nop 0
	v_fma_f32 v170, -v118, v165, 1.0
	v_fma_f32 v118, v170, v165, v165
	s_waitcnt vmcnt(11)
	v_pk_fma_f32 v[118:119], v[118:119], v[204:205], v[154:155]
	v_rcp_f32_e32 v165, v129
	s_nop 0
	v_fma_f32 v170, -v129, v165, 1.0
	v_fma_f32 v129, v170, v165, v165
	s_nop 0
	v_rcp_f32_e32 v165, v128
	s_nop 0
	v_fma_f32 v170, -v128, v165, 1.0
	v_fma_f32 v128, v170, v165, v165
	s_nop 0
	v_rcp_f32_e32 v165, v127
	s_nop 0
	v_fma_f32 v170, -v127, v165, 1.0
	v_fma_f32 v127, v170, v165, v165
	s_nop 0
	v_rcp_f32_e32 v165, v126
	s_nop 0
	v_fma_f32 v170, -v126, v165, 1.0
	v_fma_f32 v126, v170, v165, v165
	v_pk_fma_f32 v[126:127], v[126:127], v[158:159], v[150:151]
	v_rcp_f32_e32 v165, v121
	s_nop 0
	v_fma_f32 v170, -v121, v165, 1.0
	v_fma_f32 v167, v170, v165, v165
	s_nop 0
	v_rcp_f32_e32 v121, v120
	s_nop 0
	v_fma_f32 v170, -v120, v121, 1.0
	v_fma_f32 v166, v170, v121, v121
	v_pk_fma_f32 v[120:121], v[128:129], v[206:207], v[156:157]
	v_pk_fma_f32 v[128:129], v[166:167], v[160:161], v[152:153]
	global_store_dwordx4 v[200:201], v[118:121], off
	global_store_dwordx4 v[200:201], v[126:129], off offset:16
	s_nop 0
	s_nop 0
	v_mul_f32_e32 v126, v126, v126
	v_fmac_f32_e32 v126, v118, v118
	v_mul_f32_e32 v118, v127, v127
	v_fmac_f32_e32 v118, v119, v119
	v_add_f32_e32 v118, v126, v118
	v_mul_f32_e32 v119, v128, v128
	v_lshlrev_b32_e32 v126, 16, v146
	v_and_b32_e32 v127, 0xffff0000, v146
	v_fmac_f32_e32 v119, v120, v120
	v_add_f32_e32 v118, v119, v118
	v_mul_f32_e32 v119, v129, v129
	v_lshlrev_b32_e32 v128, 16, v147
	v_and_b32_e32 v129, 0xffff0000, v147
	v_fmac_f32_e32 v119, v121, v121
	v_add_f32_e32 v150, v119, v118
	v_lshlrev_b32_e32 v118, 16, v148
	v_and_b32_e32 v119, 0xffff0000, v148
	v_lshlrev_b32_e32 v120, 16, v149
	v_and_b32_e32 v121, 0xffff0000, v149
	v_pk_fma_f32 v[98:99], v[98:99], v[202:203], v[232:233] op_sel_hi:[1,0,1]
	v_pk_fma_f32 v[102:103], v[102:103], v[202:203], v[248:249] op_sel_hi:[1,0,1]
	v_mul_f32_e32 v98, 0xbfb8aa3b, v98
	v_pk_fma_f32 v[100:101], v[100:101], v[202:203], v[234:235] op_sel_hi:[1,0,1]
	v_exp_f32_e32 v146, v98
	v_mul_f32_e32 v98, 0xbfb8aa3b, v103
	v_pk_fma_f32 v[104:105], v[104:105], v[202:203], v[250:251] op_sel_hi:[1,0,1]
	v_exp_f32_e32 v103, v98
	v_mul_f32_e32 v98, 0xbfb8aa3b, v99
	v_mul_f32_e32 v99, 0xbfb8aa3b, v100
	v_mul_f32_e32 v102, 0xbfb8aa3b, v102
	v_exp_f32_e32 v147, v98
	v_mul_f32_e32 v98, 0xbfb8aa3b, v104
	v_exp_f32_e32 v100, v99
	v_mul_f32_e32 v99, 0xbfb8aa3b, v105
	v_exp_f32_e32 v102, v102
	v_exp_f32_e32 v98, v98
	v_exp_f32_e32 v99, v99
	v_mul_f32_e32 v101, 0xbfb8aa3b, v101
	v_exp_f32_e32 v101, v101
	v_pk_add_f32 v[104:105], v[98:99], 1.0 op_sel_hi:[1,0]
	v_pk_add_f32 v[98:99], v[102:103], 1.0 op_sel_hi:[1,0]
	v_pk_add_f32 v[100:101], v[100:101], 1.0 op_sel_hi:[1,0]
	s_nop 0
	v_rcp_f32_e32 v102, v99
	s_nop 0
	v_fma_f32 v149, -v99, v102, 1.0
	v_fma_f32 v99, v149, v102, v102
	s_nop 0
	v_rcp_f32_e32 v102, v98
	s_nop 0
	v_fma_f32 v149, -v98, v102, 1.0
	v_fma_f32 v98, v149, v102, v102
	s_waitcnt vmcnt(11)
; #define NTS(v, p) __builtin_nontemporal_store((v), (f32x4*)(p))
; __device__ __forceinline__ float bf_lo(unsigned w) { return __uint_as_float(w << 16); }
; __device__ __forceinline__ float bf_hi(unsigned w) { return __uint_as_float(w & 0xffff0000u); }
; __device__ __forceinline__ float sigmoidf_(float x) { return 1.0f / (1.0f + __expf(-x)); }
;     __device__ __forceinline__ void operator()(AccT& acc, const Unit& u, int wr, int wc, int fr, int fq) const {
;     ...
;             for (int bj = 0; bj < 2; ++bj) { const u32x4 pw = pv[r & 1][bj];
;                 const f32x4 b0 = *(const f32x4*)(bias + col0 + bj * 128), b1 = *(const f32x4*)(bias + col0 + bj * 128 + 4);
;                 const f32x4 p0 = (f32x4){bf_lo(pw.x), bf_hi(pw.x), bf_lo(pw.y), bf_hi(pw.y)}, p1 = (f32x4){bf_lo(pw.z), bf_hi(pw.z), bf_lo(pw.w), bf_hi(pw.w)};
;                 f32x4 g0 = acc[ai][bj][m][0] * rstd + b0, g1 = acc[ai][bj][m][1] * rstd + b1;
; #pragma unroll
;                 for (int j = 0; j < 4; ++j) { g0[j] = sigmoidf_(g0[j]); g1[j] = sigmoidf_(g1[j]); }
;                 const f32x4 v0 = hv[r & 1][2 * bj] + p0 * g0, v1 = hv[r & 1][2 * bj + 1] + p1 * g1;
;                 NTS(v0, hp + bj * 128); NTS(v1, hp + bj * 128 + 4);
; #pragma unroll
;                 for (int j = 0; j < 4; ++j) ss += v0[j] * v0[j] + v1[j] * v1[j]; }
;             ss += __shfl_xor(ss, 16); ss += __shfl_xor(ss, 32);
;             if (fq == 0) unsafeAtomicAdd(rss3 + row, ss); __builtin_amdgcn_sched_barrier(0); }
	v_pk_fma_f32 v[98:99], v[98:99], v[126:127], v[138:139]
	v_rcp_f32_e32 v102, v105
	s_nop 0
	v_fma_f32 v149, -v105, v102, 1.0
	v_fma_f32 v103, v149, v102, v102
	s_nop 0
	v_rcp_f32_e32 v149, v104
	s_nop 0
	v_fma_f32 v151, -v104, v149, 1.0
	v_fma_f32 v102, v151, v149, v149
	v_pk_add_f32 v[104:105], v[146:147], 1.0 op_sel_hi:[1,0]
	s_nop 0
	s_nop 0
	v_rcp_f32_e32 v146, v105
	s_nop 0
	v_fma_f32 v149, -v105, v146, 1.0
	v_fma_f32 v147, v149, v146, v146
	s_nop 0
	v_rcp_f32_e32 v105, v104
	s_nop 0
	v_fma_f32 v149, -v104, v105, 1.0
	v_fma_f32 v146, v149, v105, v105
	s_nop 0
	v_rcp_f32_e32 v104, v101
	s_nop 0
	v_fma_f32 v149, -v101, v104, 1.0
	v_fma_f32 v105, v149, v104, v104
	s_nop 0
	v_rcp_f32_e32 v101, v100
	s_nop 0
	v_fma_f32 v149, -v100, v101, 1.0
	v_fma_f32 v104, v149, v101, v101
	v_pk_fma_f32 v[100:101], v[102:103], v[128:129], v[140:141]
	v_pk_fma_f32 v[102:103], v[146:147], v[118:119], v[130:131]
	v_pk_fma_f32 v[104:105], v[104:105], v[120:121], v[132:133]
	global_store_dwordx4 v[200:201], v[98:101], off offset:512
	global_store_dwordx4 v[200:201], v[102:105], off offset:528
	s_nop 1
	v_mul_f32_e32 v102, v102, v102
	v_fmac_f32_e32 v102, v98, v98
	v_add_f32_e32 v98, v150, v102
	v_mul_f32_e32 v102, v103, v103
	v_fmac_f32_e32 v102, v99, v99
	v_mul_f32_e32 v99, v104, v104
	v_add_f32_e32 v98, v102, v98
	v_fmac_f32_e32 v99, v100, v100
	v_add_f32_e32 v98, v99, v98
	v_mul_f32_e32 v99, v105, v105
	v_fmac_f32_e32 v99, v101, v101
	v_add_f32_e32 v98, v99, v98
	ds_bpermute_b32 v99, v225, v98
	s_waitcnt lgkmcnt(0)
	v_add_f32_e32 v98, v98, v99
	ds_bpermute_b32 v99, v226, v98
	s_and_saveexec_b64 s[2:3], s[42:43]
	s_cbranch_execz .LBB0_785
	v_lshl_add_u64 v[100:101], v[198:199], 2, s[36:37]
	s_waitcnt lgkmcnt(0)
	v_add_f32_e32 v98, v98, v99
	global_atomic_add_f32 v[100:101], v98, off
.LBB0_785:
	s_or_b64 exec, exec, s[2:3]
	v_add_u32_e32 v146, 48, v186
	v_ashrrev_i32_e32 v147, 31, v146
	s_waitcnt lgkmcnt(0)
	v_lshlrev_b64 v[98:99], 12, v[146:147]
	v_lshl_add_u64 v[98:99], s[22:23], 0, v[98:99]
	v_add_co_u32_e32 v118, vcc, 0x6000, v190
	v_lshl_add_u64 v[148:149], v[192:193], 2, v[98:99]
	s_nop 0
	v_addc_co_u32_e32 v119, vcc, 0, v191, vcc
	global_load_dwordx4 v[126:129], v[148:149], off offset:16 nt
	global_load_dwordx4 v[130:133], v[148:149], off nt
	global_load_dwordx4 v[98:101], v[148:149], off offset:528 nt
	global_load_dwordx4 v[102:105], v[148:149], off offset:512 nt
	global_load_dwordx4 v[138:141], v[118:119], off
	s_nop 0
	global_load_dwordx4 v[118:121], v[118:119], off offset:256
	s_nop 0
	global_load_dword v151, v[188:189], off offset:192
	s_waitcnt vmcnt(11)
	v_fmamk_f32 v150, v164, 0x3a800000, v210
	v_cmp_gt_f32_e32 vcc, s30, v150
	v_mul_f32_e32 v152, 0x4b800000, v150
	v_and_b32_e32 v153, 0xffff0000, v142
	v_cndmask_b32_e32 v150, v150, v152, vcc
	v_rsq_f32_e32 v150, v150
	v_lshlrev_b32_e32 v154, 16, v143
	v_and_b32_e32 v155, 0xffff0000, v143
	v_and_b32_e32 v143, 0xffff0000, v144
	v_mul_f32_e32 v152, 0x45800000, v150
	v_cndmask_b32_e32 v150, v150, v152, vcc
	v_lshlrev_b32_e32 v152, 16, v142
	v_lshlrev_b32_e32 v142, 16, v144
	v_lshlrev_b32_e32 v144, 16, v145
	v_and_b32_e32 v145, 0xffff0000, v145
	v_pk_fma_f32 v[90:91], v[90:91], v[150:151], v[244:245] op_sel_hi:[1,0,1]
	v_pk_fma_f32 v[94:95], v[94:95], v[150:151], v[240:241] op_sel_hi:[1,0,1]
	v_mul_f32_e32 v90, 0xbfb8aa3b, v90
	v_mul_f32_e32 v94, 0xbfb8aa3b, v94
	v_pk_fma_f32 v[92:93], v[92:93], v[150:151], v[246:247] op_sel_hi:[1,0,1]
	v_exp_f32_e32 v156, v94
	v_exp_f32_e32 v94, v90
	v_mul_f32_e32 v90, 0xbfb8aa3b, v95
	v_pk_fma_f32 v[96:97], v[96:97], v[150:151], v[242:243] op_sel_hi:[1,0,1]
	v_exp_f32_e32 v157, v90
	v_mul_f32_e32 v90, 0xbfb8aa3b, v91
	v_mul_f32_e32 v91, 0xbfb8aa3b, v92
	v_exp_f32_e32 v95, v90
	v_mul_f32_e32 v90, 0xbfb8aa3b, v96
	v_exp_f32_e32 v92, v91
	v_mul_f32_e32 v91, 0xbfb8aa3b, v97
	v_exp_f32_e32 v90, v90
	v_exp_f32_e32 v91, v91
	v_pk_add_f32 v[94:95], v[94:95], 1.0 op_sel_hi:[1,0]
	v_mul_f32_e32 v93, 0xbfb8aa3b, v93
	v_exp_f32_e32 v93, v93
	v_pk_add_f32 v[96:97], v[90:91], 1.0 op_sel_hi:[1,0]
	v_pk_add_f32 v[90:91], v[156:157], 1.0 op_sel_hi:[1,0]
	v_pk_add_f32 v[92:93], v[92:93], 1.0 op_sel_hi:[1,0]
	s_nop 0
	v_rcp_f32_e32 v156, v91
	s_nop 0
	v_fma_f32 v159, -v91, v156, 1.0
	v_fma_f32 v91, v159, v156, v156
	s_nop 0
	v_rcp_f32_e32 v156, v90
	s_nop 0
	v_fma_f32 v159, -v90, v156, 1.0
	v_fma_f32 v90, v159, v156, v156
	v_pk_fma_f32 v[90:91], v[90:91], v[152:153], v[134:135]
	v_rcp_f32_e32 v156, v97
	s_nop 0
	v_fma_f32 v159, -v97, v156, 1.0
	v_fma_f32 v97, v159, v156, v156
	s_nop 0
	v_rcp_f32_e32 v156, v96
	s_nop 0
	v_fma_f32 v159, -v96, v156, 1.0
	v_fma_f32 v96, v159, v156, v156
	s_nop 0
	v_rcp_f32_e32 v156, v95
	s_nop 0
	v_fma_f32 v159, -v95, v156, 1.0
	v_fma_f32 v95, v159, v156, v156
	s_nop 0
	v_rcp_f32_e32 v156, v94
	s_nop 0
	v_fma_f32 v159, -v94, v156, 1.0
	v_fma_f32 v94, v159, v156, v156
	v_pk_fma_f32 v[94:95], v[94:95], v[142:143], v[122:123]
	v_rcp_f32_e32 v156, v93
	s_nop 0
	v_fma_f32 v159, -v93, v156, 1.0
	v_fma_f32 v157, v159, v156, v156
	s_nop 0
	v_rcp_f32_e32 v93, v92
	s_nop 0
	v_fma_f32 v159, -v92, v93, 1.0
	v_fma_f32 v156, v159, v93, v93
	v_pk_fma_f32 v[92:93], v[96:97], v[154:155], v[136:137]
	v_pk_fma_f32 v[96:97], v[156:157], v[144:145], v[124:125]
	global_store_dwordx4 v[196:197], v[90:93], off
	global_store_dwordx4 v[196:197], v[94:97], off offset:16
	s_nop 0
	s_nop 0
	v_mul_f32_e32 v94, v94, v94
	v_fmac_f32_e32 v94, v90, v90
	v_mul_f32_e32 v90, v95, v95
	v_fmac_f32_e32 v90, v91, v91
	v_add_f32_e32 v90, v94, v90
	v_mul_f32_e32 v91, v96, v96
	v_lshlrev_b32_e32 v94, 16, v114
	v_and_b32_e32 v95, 0xffff0000, v114
	v_fmac_f32_e32 v91, v92, v92
	v_add_f32_e32 v90, v91, v90
; #define NTL(p) __builtin_nontemporal_load((const f32x4*)(p))
; #define NTS(v, p) __builtin_nontemporal_store((v), (f32x4*)(p))
; __device__ __forceinline__ float bf_lo(unsigned w) { return __uint_as_float(w << 16); }
; __device__ __forceinline__ float bf_hi(unsigned w) { return __uint_as_float(w & 0xffff0000u); }
; __device__ __forceinline__ float sigmoidf_(float x) { return 1.0f / (1.0f + __expf(-x)); }
;     __device__ __forceinline__ void operator()(AccT& acc, const Unit& u, int wr, int wc, int fr, int fq) const {
;     ...
;         for (int r = 0; r < 8; ++r) { const int ai = r >> 2, m = r & 3; const int row = row0 + ai * 128 + m * 16;
;             if (r < 7) { const int rn = row0 + ((r + 1) >> 2) * 128 + ((r + 1) & 3) * 16; const float* hn = H + (size_t)rn * DM + col0; const bf16_t* pn = ppbase + (((r + 1) >> 2) * 128 + ((r + 1) & 3) * 16) * 256;
;                 hv[(r + 1) & 1][0] = NTL(hn); hv[(r + 1) & 1][1] = NTL(hn + 4); hv[(r + 1) & 1][2] = NTL(hn + 128); hv[(r + 1) & 1][3] = NTL(hn + 132);
;                 pv[(r + 1) & 1][0] = *(const u32x4*)pn; pv[(r + 1) & 1][1] = *(const u32x4*)(pn + 128); rs[(r + 1) & 1] = rss2[rn]; }
;             float* hp = H + (size_t)row * DM + col0; float ss = 0.f; const float rstd = rsqrtf(rs[r & 1] * (1.0f / DM) + 1e-6f);
; #pragma unroll
;             for (int bj = 0; bj < 2; ++bj) { const u32x4 pw = pv[r & 1][bj];
;                 const f32x4 b0 = *(const f32x4*)(bias + col0 + bj * 128), b1 = *(const f32x4*)(bias + col0 + bj * 128 + 4);
;                 const f32x4 p0 = (f32x4){bf_lo(pw.x), bf_hi(pw.x), bf_lo(pw.y), bf_hi(pw.y)}, p1 = (f32x4){bf_lo(pw.z), bf_hi(pw.z), bf_lo(pw.w), bf_hi(pw.w)};
;                 f32x4 g0 = acc[ai][bj][m][0] * rstd + b0, g1 = acc[ai][bj][m][1] * rstd + b1;
; #pragma unroll
;                 for (int j = 0; j < 4; ++j) { g0[j] = sigmoidf_(g0[j]); g1[j] = sigmoidf_(g1[j]); }
;                 const f32x4 v0 = hv[r & 1][2 * bj] + p0 * g0, v1 = hv[r & 1][2 * bj + 1] + p1 * g1;
;                 NTS(v0, hp + bj * 128); NTS(v1, hp + bj * 128 + 4);
; #pragma unroll
;                 for (int j = 0; j < 4; ++j) ss += v0[j] * v0[j] + v1[j] * v1[j]; }
;             ss += __shfl_xor(ss, 16); ss += __shfl_xor(ss, 32);
;             if (fq == 0) unsafeAtomicAdd(rss3 + row, ss); __builtin_amdgcn_sched_barrier(0); }
	v_mul_f32_e32 v91, v97, v97
	v_lshlrev_b32_e32 v96, 16, v115
	v_and_b32_e32 v97, 0xffff0000, v115
	v_fmac_f32_e32 v91, v93, v93
	v_add_f32_e32 v122, v91, v90
	v_lshlrev_b32_e32 v90, 16, v116
	v_and_b32_e32 v91, 0xffff0000, v116
	v_lshlrev_b32_e32 v92, 16, v117
	v_and_b32_e32 v93, 0xffff0000, v117
	v_pk_fma_f32 v[82:83], v[82:83], v[150:151], v[232:233] op_sel_hi:[1,0,1]
	v_pk_fma_f32 v[86:87], v[86:87], v[150:151], v[248:249] op_sel_hi:[1,0,1]
	v_mul_f32_e32 v82, 0xbfb8aa3b, v82
	v_pk_fma_f32 v[84:85], v[84:85], v[150:151], v[234:235] op_sel_hi:[1,0,1]
	v_exp_f32_e32 v114, v82
	v_mul_f32_e32 v82, 0xbfb8aa3b, v87
	v_pk_fma_f32 v[88:89], v[88:89], v[150:151], v[250:251] op_sel_hi:[1,0,1]
	v_exp_f32_e32 v87, v82
	v_mul_f32_e32 v82, 0xbfb8aa3b, v83
	v_mul_f32_e32 v83, 0xbfb8aa3b, v84
	v_mul_f32_e32 v86, 0xbfb8aa3b, v86
	v_exp_f32_e32 v115, v82
	v_mul_f32_e32 v82, 0xbfb8aa3b, v88
	v_exp_f32_e32 v84, v83
	v_mul_f32_e32 v83, 0xbfb8aa3b, v89
	v_exp_f32_e32 v86, v86
	v_exp_f32_e32 v82, v82
	v_exp_f32_e32 v83, v83
	v_mul_f32_e32 v85, 0xbfb8aa3b, v85
	v_exp_f32_e32 v85, v85
	v_pk_add_f32 v[88:89], v[82:83], 1.0 op_sel_hi:[1,0]
	v_pk_add_f32 v[82:83], v[86:87], 1.0 op_sel_hi:[1,0]
	v_pk_add_f32 v[84:85], v[84:85], 1.0 op_sel_hi:[1,0]
	s_nop 0
	v_rcp_f32_e32 v86, v83
	s_nop 0
	v_fma_f32 v117, -v83, v86, 1.0
	v_fma_f32 v83, v117, v86, v86
	s_nop 0
	v_rcp_f32_e32 v86, v82
	s_nop 0
	v_fma_f32 v117, -v82, v86, 1.0
	v_fma_f32 v82, v117, v86, v86
	v_pk_fma_f32 v[82:83], v[82:83], v[94:95], v[110:111]
	v_rcp_f32_e32 v86, v89
	s_nop 0
	v_fma_f32 v117, -v89, v86, 1.0
	v_fma_f32 v87, v117, v86, v86
	s_nop 0
	v_rcp_f32_e32 v117, v88
	s_nop 0
	v_fma_f32 v123, -v88, v117, 1.0
	v_fma_f32 v86, v123, v117, v117
	v_pk_add_f32 v[88:89], v[114:115], 1.0 op_sel_hi:[1,0]
	s_nop 0
	s_nop 0
	v_rcp_f32_e32 v114, v89
	s_nop 0
	v_fma_f32 v117, -v89, v114, 1.0
	v_fma_f32 v115, v117, v114, v114
	s_nop 0
	v_rcp_f32_e32 v89, v88
	s_nop 0
	v_fma_f32 v117, -v88, v89, 1.0
	v_fma_f32 v114, v117, v89, v89
	s_nop 0
	v_rcp_f32_e32 v88, v85
	s_nop 0
	v_fma_f32 v117, -v85, v88, 1.0
	v_fma_f32 v89, v117, v88, v88
	s_nop 0
	v_rcp_f32_e32 v85, v84
	s_nop 0
	v_fma_f32 v117, -v84, v85, 1.0
	v_fma_f32 v88, v117, v85, v85
	v_pk_fma_f32 v[84:85], v[86:87], v[96:97], v[112:113]
	v_pk_fma_f32 v[86:87], v[114:115], v[90:91], v[106:107]
	v_pk_fma_f32 v[88:89], v[88:89], v[92:93], v[108:109]
	global_store_dwordx4 v[196:197], v[82:85], off offset:512
	global_store_dwordx4 v[196:197], v[86:89], off offset:528
	s_nop 1
	v_mul_f32_e32 v86, v86, v86
	v_fmac_f32_e32 v86, v82, v82
	v_add_f32_e32 v82, v122, v86
	v_mul_f32_e32 v86, v87, v87
	v_fmac_f32_e32 v86, v83, v83
	v_mul_f32_e32 v83, v88, v88
	v_add_f32_e32 v82, v86, v82
	v_fmac_f32_e32 v83, v84, v84
	v_add_f32_e32 v82, v83, v82
	v_mul_f32_e32 v83, v89, v89
	v_fmac_f32_e32 v83, v85, v85
	v_add_f32_e32 v82, v83, v82
	ds_bpermute_b32 v83, v225, v82
	s_waitcnt lgkmcnt(0)
	v_add_f32_e32 v82, v82, v83
	ds_bpermute_b32 v83, v226, v82
	s_and_saveexec_b64 s[2:3], s[42:43]
	s_cbranch_execz .LBB0_787
	v_lshl_add_u64 v[84:85], v[194:195], 2, s[36:37]
	s_waitcnt lgkmcnt(0)
	v_add_f32_e32 v82, v82, v83
	global_atomic_add_f32 v[84:85], v82, off
.LBB0_787:
	s_or_b64 exec, exec, s[2:3]
	v_add_u32_e32 v114, 0x80, v186
	v_ashrrev_i32_e32 v115, 31, v114
	s_waitcnt lgkmcnt(0)
	v_lshlrev_b64 v[82:83], 12, v[114:115]
	v_lshl_add_u64 v[82:83], s[22:23], 0, v[82:83]
	v_add_co_u32_e32 v90, vcc, 0x10000, v190
	v_lshl_add_u64 v[122:123], v[192:193], 2, v[82:83]
	s_nop 0
	v_addc_co_u32_e32 v91, vcc, 0, v191, vcc
	global_load_dwordx4 v[94:97], v[122:123], off offset:16 nt
	global_load_dwordx4 v[106:109], v[122:123], off nt
	global_load_dwordx4 v[82:85], v[122:123], off offset:528 nt
	global_load_dwordx4 v[86:89], v[122:123], off offset:512 nt
	global_load_dwordx4 v[110:113], v[90:91], off
	s_nop 0
	global_load_dwordx4 v[90:93], v[90:91], off offset:256
	s_nop 0
	global_load_dword v142, v[188:189], off offset:512
	s_waitcnt vmcnt(11)
	v_fmamk_f32 v116, v151, 0x3a800000, v210
	v_cmp_gt_f32_e32 vcc, s30, v116
	v_mul_f32_e32 v117, 0x4b800000, v116
	v_lshlrev_b32_e32 v124, 16, v140
	v_cndmask_b32_e32 v116, v116, v117, vcc
	v_rsq_f32_e32 v116, v116
	v_and_b32_e32 v125, 0xffff0000, v140
	v_lshlrev_b32_e32 v134, 16, v141
	v_and_b32_e32 v135, 0xffff0000, v141
	v_mul_f32_e32 v117, 0x45800000, v116
	v_cndmask_b32_e32 v116, v116, v117, vcc
	v_lshlrev_b32_e32 v136, 16, v138
	v_and_b32_e32 v137, 0xffff0000, v138
	v_lshlrev_b32_e32 v138, 16, v139
	v_and_b32_e32 v139, 0xffff0000, v139
	v_pk_fma_f32 v[74:75], v[74:75], v[116:117], v[244:245] op_sel_hi:[1,0,1]
	v_pk_fma_f32 v[78:79], v[78:79], v[116:117], v[240:241] op_sel_hi:[1,0,1]
	v_mul_f32_e32 v74, 0xbfb8aa3b, v74
	v_mul_f32_e32 v78, 0xbfb8aa3b, v78
	v_pk_fma_f32 v[76:77], v[76:77], v[116:117], v[246:247] op_sel_hi:[1,0,1]
	v_exp_f32_e32 v140, v78
	v_exp_f32_e32 v78, v74
	v_mul_f32_e32 v74, 0xbfb8aa3b, v79
	v_pk_fma_f32 v[80:81], v[80:81], v[116:117], v[242:243] op_sel_hi:[1,0,1]
	v_exp_f32_e32 v141, v74
	v_mul_f32_e32 v74, 0xbfb8aa3b, v75
	v_mul_f32_e32 v75, 0xbfb8aa3b, v76
	v_exp_f32_e32 v79, v74
	v_mul_f32_e32 v74, 0xbfb8aa3b, v80
	v_exp_f32_e32 v76, v75
	v_mul_f32_e32 v75, 0xbfb8aa3b, v81
	v_exp_f32_e32 v74, v74
	v_exp_f32_e32 v75, v75
	v_pk_add_f32 v[78:79], v[78:79], 1.0 op_sel_hi:[1,0]
	v_mul_f32_e32 v77, 0xbfb8aa3b, v77
	v_exp_f32_e32 v77, v77
	v_pk_add_f32 v[80:81], v[74:75], 1.0 op_sel_hi:[1,0]
	v_pk_add_f32 v[74:75], v[140:141], 1.0 op_sel_hi:[1,0]
	v_pk_add_f32 v[76:77], v[76:77], 1.0 op_sel_hi:[1,0]
	s_nop 0
	v_rcp_f32_e32 v117, v75
	s_nop 0
	v_fma_f32 v143, -v75, v117, 1.0
	v_fma_f32 v75, v143, v117, v117
	s_nop 0
	v_rcp_f32_e32 v117, v74
; #define NTS(v, p) __builtin_nontemporal_store((v), (f32x4*)(p))
; __device__ __forceinline__ float bf_lo(unsigned w) { return __uint_as_float(w << 16); }
; __device__ __forceinline__ float bf_hi(unsigned w) { return __uint_as_float(w & 0xffff0000u); }
; __device__ __forceinline__ float sigmoidf_(float x) { return 1.0f / (1.0f + __expf(-x)); }
;     __device__ __forceinline__ void operator()(AccT& acc, const Unit& u, int wr, int wc, int fr, int fq) const {
;     ...
;             float* hp = H + (size_t)row * DM + col0; float ss = 0.f; const float rstd = rsqrtf(rs[r & 1] * (1.0f / DM) + 1e-6f);
; #pragma unroll
;             for (int bj = 0; bj < 2; ++bj) { const u32x4 pw = pv[r & 1][bj];
;                 const f32x4 b0 = *(const f32x4*)(bias + col0 + bj * 128), b1 = *(const f32x4*)(bias + col0 + bj * 128 + 4);
;                 const f32x4 p0 = (f32x4){bf_lo(pw.x), bf_hi(pw.x), bf_lo(pw.y), bf_hi(pw.y)}, p1 = (f32x4){bf_lo(pw.z), bf_hi(pw.z), bf_lo(pw.w), bf_hi(pw.w)};
;                 f32x4 g0 = acc[ai][bj][m][0] * rstd + b0, g1 = acc[ai][bj][m][1] * rstd + b1;
; #pragma unroll
;                 for (int j = 0; j < 4; ++j) { g0[j] = sigmoidf_(g0[j]); g1[j] = sigmoidf_(g1[j]); }
;                 const f32x4 v0 = hv[r & 1][2 * bj] + p0 * g0, v1 = hv[r & 1][2 * bj + 1] + p1 * g1;
;                 NTS(v0, hp + bj * 128); NTS(v1, hp + bj * 128 + 4);
; #pragma unroll
;                 for (int j = 0; j < 4; ++j) ss += v0[j] * v0[j] + v1[j] * v1[j]; }
;             ss += __shfl_xor(ss, 16); ss += __shfl_xor(ss, 32);
;             if (fq == 0) unsafeAtomicAdd(rss3 + row, ss); __builtin_amdgcn_sched_barrier(0); }
	s_nop 0
	v_fma_f32 v143, -v74, v117, 1.0
	v_fma_f32 v74, v143, v117, v117
	v_pk_fma_f32 v[74:75], v[74:75], v[136:137], v[130:131]
	v_rcp_f32_e32 v117, v81
	s_nop 0
	v_fma_f32 v143, -v81, v117, 1.0
	v_fma_f32 v81, v143, v117, v117
	s_nop 0
	v_rcp_f32_e32 v117, v80
	s_nop 0
	v_fma_f32 v143, -v80, v117, 1.0
	v_fma_f32 v80, v143, v117, v117
	s_nop 0
	v_rcp_f32_e32 v117, v79
	s_nop 0
	v_fma_f32 v143, -v79, v117, 1.0
	v_fma_f32 v79, v143, v117, v117
	s_nop 0
	v_rcp_f32_e32 v117, v78
	s_nop 0
	v_fma_f32 v143, -v78, v117, 1.0
	v_fma_f32 v78, v143, v117, v117
	v_pk_fma_f32 v[78:79], v[78:79], v[124:125], v[126:127]
	v_rcp_f32_e32 v117, v77
	s_nop 0
	v_fma_f32 v143, -v77, v117, 1.0
	v_fma_f32 v141, v143, v117, v117
	s_nop 0
	v_rcp_f32_e32 v77, v76
	s_nop 0
	v_fma_f32 v143, -v76, v77, 1.0
	v_fma_f32 v140, v143, v77, v77
	v_pk_fma_f32 v[76:77], v[80:81], v[138:139], v[132:133]
	v_pk_fma_f32 v[80:81], v[140:141], v[134:135], v[128:129]
	global_store_dwordx4 v[148:149], v[74:77], off
	global_store_dwordx4 v[148:149], v[78:81], off offset:16
	s_nop 0
	s_nop 0
	v_mul_f32_e32 v78, v78, v78
	v_fmac_f32_e32 v78, v74, v74
	v_mul_f32_e32 v74, v79, v79
	v_fmac_f32_e32 v74, v75, v75
	v_mul_f32_e32 v75, v80, v80
	v_add_f32_e32 v74, v78, v74
	v_fmac_f32_e32 v75, v76, v76
	v_add_f32_e32 v74, v75, v74
	v_mul_f32_e32 v75, v81, v81
	v_fmac_f32_e32 v75, v77, v77
	v_add_f32_e32 v117, v75, v74
	v_lshlrev_b32_e32 v78, 16, v118
	v_and_b32_e32 v79, 0xffff0000, v118
	v_lshlrev_b32_e32 v80, 16, v119
	v_and_b32_e32 v81, 0xffff0000, v119
	v_lshlrev_b32_e32 v74, 16, v120
	v_and_b32_e32 v75, 0xffff0000, v120
	v_lshlrev_b32_e32 v76, 16, v121
	v_and_b32_e32 v77, 0xffff0000, v121
	v_pk_fma_f32 v[66:67], v[66:67], v[116:117], v[232:233] op_sel_hi:[1,0,1]
	v_pk_fma_f32 v[70:71], v[70:71], v[116:117], v[248:249] op_sel_hi:[1,0,1]
	v_mul_f32_e32 v66, 0xbfb8aa3b, v66
	v_pk_fma_f32 v[68:69], v[68:69], v[116:117], v[234:235] op_sel_hi:[1,0,1]
	v_exp_f32_e32 v118, v66
	v_mul_f32_e32 v66, 0xbfb8aa3b, v71
	v_pk_fma_f32 v[72:73], v[72:73], v[116:117], v[250:251] op_sel_hi:[1,0,1]
	v_exp_f32_e32 v71, v66
	v_mul_f32_e32 v66, 0xbfb8aa3b, v67
	v_mul_f32_e32 v67, 0xbfb8aa3b, v68
	v_mul_f32_e32 v70, 0xbfb8aa3b, v70
	v_exp_f32_e32 v119, v66
	v_mul_f32_e32 v66, 0xbfb8aa3b, v72
	v_exp_f32_e32 v68, v67
	v_mul_f32_e32 v67, 0xbfb8aa3b, v73
	v_exp_f32_e32 v70, v70
	v_exp_f32_e32 v66, v66
	v_exp_f32_e32 v67, v67
	v_mul_f32_e32 v69, 0xbfb8aa3b, v69
	v_exp_f32_e32 v69, v69
	v_pk_add_f32 v[72:73], v[66:67], 1.0 op_sel_hi:[1,0]
	v_pk_add_f32 v[66:67], v[70:71], 1.0 op_sel_hi:[1,0]
	v_pk_add_f32 v[68:69], v[68:69], 1.0 op_sel_hi:[1,0]
	s_nop 0
	v_rcp_f32_e32 v70, v67
	s_nop 0
	v_fma_f32 v120, -v67, v70, 1.0
	v_fma_f32 v67, v120, v70, v70
	s_nop 0
	v_rcp_f32_e32 v70, v66
	s_nop 0
	v_fma_f32 v120, -v66, v70, 1.0
	v_fma_f32 v66, v120, v70, v70
	v_pk_fma_f32 v[66:67], v[66:67], v[78:79], v[102:103]
	v_rcp_f32_e32 v70, v73
	s_nop 0
	v_fma_f32 v120, -v73, v70, 1.0
	v_fma_f32 v71, v120, v70, v70
	s_nop 0
	v_rcp_f32_e32 v120, v72
	s_nop 0
	v_fma_f32 v121, -v72, v120, 1.0
	v_fma_f32 v70, v121, v120, v120
	v_pk_add_f32 v[72:73], v[118:119], 1.0 op_sel_hi:[1,0]
	s_nop 0
	s_nop 0
	v_rcp_f32_e32 v116, v73
	s_nop 0
	v_fma_f32 v120, -v73, v116, 1.0
	v_fma_f32 v119, v120, v116, v116
	s_nop 0
	v_rcp_f32_e32 v73, v72
	s_nop 0
	v_fma_f32 v120, -v72, v73, 1.0
	v_fma_f32 v118, v120, v73, v73
	s_nop 0
	v_rcp_f32_e32 v72, v69
	s_nop 0
	v_fma_f32 v120, -v69, v72, 1.0
	v_fma_f32 v73, v120, v72, v72
	s_nop 0
	v_rcp_f32_e32 v69, v68
	s_nop 0
	v_fma_f32 v120, -v68, v69, 1.0
	v_fma_f32 v72, v120, v69, v69
	v_pk_fma_f32 v[68:69], v[70:71], v[80:81], v[104:105]
	v_pk_fma_f32 v[70:71], v[118:119], v[74:75], v[98:99]
	v_pk_fma_f32 v[72:73], v[72:73], v[76:77], v[100:101]
	global_store_dwordx4 v[148:149], v[66:69], off offset:512
	global_store_dwordx4 v[148:149], v[70:73], off offset:528
	s_nop 1
	v_mul_f32_e32 v70, v70, v70
	v_fmac_f32_e32 v70, v66, v66
	v_add_f32_e32 v66, v117, v70
	v_mul_f32_e32 v70, v71, v71
	v_fmac_f32_e32 v70, v67, v67
	v_mul_f32_e32 v67, v72, v72
	v_add_f32_e32 v66, v70, v66
	v_fmac_f32_e32 v67, v68, v68
	v_add_f32_e32 v66, v67, v66
	v_mul_f32_e32 v67, v73, v73
	v_fmac_f32_e32 v67, v69, v69
	v_add_f32_e32 v66, v67, v66
	ds_bpermute_b32 v67, v225, v66
	s_waitcnt lgkmcnt(0)
	v_add_f32_e32 v66, v66, v67
	ds_bpermute_b32 v67, v226, v66
	s_and_saveexec_b64 s[2:3], s[42:43]
	s_cbranch_execz .LBB0_789
	v_lshl_add_u64 v[68:69], v[146:147], 2, s[36:37]
	s_waitcnt lgkmcnt(0)
	v_add_f32_e32 v66, v66, v67
	global_atomic_add_f32 v[68:69], v66, off
; #define NTL(p) __builtin_nontemporal_load((const f32x4*)(p))
; #define NTS(v, p) __builtin_nontemporal_store((v), (f32x4*)(p))
; __device__ __forceinline__ float bf_lo(unsigned w) { return __uint_as_float(w << 16); }
; __device__ __forceinline__ float bf_hi(unsigned w) { return __uint_as_float(w & 0xffff0000u); }
; __device__ __forceinline__ float sigmoidf_(float x) { return 1.0f / (1.0f + __expf(-x)); }
;     __device__ __forceinline__ void operator()(AccT& acc, const Unit& u, int wr, int wc, int fr, int fq) const {
;     ...
;         for (int r = 0; r < 8; ++r) { const int ai = r >> 2, m = r & 3; const int row = row0 + ai * 128 + m * 16;
;             if (r < 7) { const int rn = row0 + ((r + 1) >> 2) * 128 + ((r + 1) & 3) * 16; const float* hn = H + (size_t)rn * DM + col0; const bf16_t* pn = ppbase + (((r + 1) >> 2) * 128 + ((r + 1) & 3) * 16) * 256;
;                 hv[(r + 1) & 1][0] = NTL(hn); hv[(r + 1) & 1][1] = NTL(hn + 4); hv[(r + 1) & 1][2] = NTL(hn + 128); hv[(r + 1) & 1][3] = NTL(hn + 132);
;                 pv[(r + 1) & 1][0] = *(const u32x4*)pn; pv[(r + 1) & 1][1] = *(const u32x4*)(pn + 128); rs[(r + 1) & 1] = rss2[rn]; }
;             float* hp = H + (size_t)row * DM + col0; float ss = 0.f; const float rstd = rsqrtf(rs[r & 1] * (1.0f / DM) + 1e-6f);
; #pragma unroll
;             for (int bj = 0; bj < 2; ++bj) { const u32x4 pw = pv[r & 1][bj];
;                 const f32x4 b0 = *(const f32x4*)(bias + col0 + bj * 128), b1 = *(const f32x4*)(bias + col0 + bj * 128 + 4);
;                 const f32x4 p0 = (f32x4){bf_lo(pw.x), bf_hi(pw.x), bf_lo(pw.y), bf_hi(pw.y)}, p1 = (f32x4){bf_lo(pw.z), bf_hi(pw.z), bf_lo(pw.w), bf_hi(pw.w)};
;                 f32x4 g0 = acc[ai][bj][m][0] * rstd + b0, g1 = acc[ai][bj][m][1] * rstd + b1;
; #pragma unroll
;                 for (int j = 0; j < 4; ++j) { g0[j] = sigmoidf_(g0[j]); g1[j] = sigmoidf_(g1[j]); }
;                 const f32x4 v0 = hv[r & 1][2 * bj] + p0 * g0, v1 = hv[r & 1][2 * bj + 1] + p1 * g1;
;                 NTS(v0, hp + bj * 128); NTS(v1, hp + bj * 128 + 4);
; #pragma unroll
;                 for (int j = 0; j < 4; ++j) ss += v0[j] * v0[j] + v1[j] * v1[j]; }
;             ss += __shfl_xor(ss, 16); ss += __shfl_xor(ss, 32);
;             if (fq == 0) unsafeAtomicAdd(rss3 + row, ss); __builtin_amdgcn_sched_barrier(0); }
.LBB0_789:
	s_or_b64 exec, exec, s[2:3]
	v_add_u32_e32 v116, 0x90, v186
	v_ashrrev_i32_e32 v117, 31, v116
	s_waitcnt lgkmcnt(0)
	v_lshlrev_b64 v[66:67], 12, v[116:117]
	v_lshl_add_u64 v[66:67], s[22:23], 0, v[66:67]
	v_add_co_u32_e32 v74, vcc, 0x12000, v190
	v_lshl_add_u64 v[118:119], v[192:193], 2, v[66:67]
	s_nop 0
	v_addc_co_u32_e32 v75, vcc, 0, v191, vcc
	global_load_dwordx4 v[78:81], v[118:119], off offset:16 nt
	global_load_dwordx4 v[98:101], v[118:119], off nt
	global_load_dwordx4 v[66:69], v[118:119], off offset:528 nt
	global_load_dwordx4 v[70:73], v[118:119], off offset:512 nt
	global_load_dwordx4 v[102:105], v[74:75], off
	s_nop 0
	global_load_dwordx4 v[74:77], v[74:75], off offset:256
	s_nop 0
	global_load_dword v121, v[188:189], off offset:576
	s_waitcnt vmcnt(11)
	v_fmamk_f32 v120, v142, 0x3a800000, v210
	v_cmp_gt_f32_e32 vcc, s30, v120
	v_mul_f32_e32 v124, 0x4b800000, v120
	v_and_b32_e32 v125, 0xffff0000, v110
	v_cndmask_b32_e32 v120, v120, v124, vcc
	v_rsq_f32_e32 v120, v120
	v_lshlrev_b32_e32 v126, 16, v111
	v_and_b32_e32 v127, 0xffff0000, v111
	v_and_b32_e32 v111, 0xffff0000, v112
	v_mul_f32_e32 v124, 0x45800000, v120
	v_cndmask_b32_e32 v120, v120, v124, vcc
	v_lshlrev_b32_e32 v124, 16, v110
	v_lshlrev_b32_e32 v110, 16, v112
	v_lshlrev_b32_e32 v112, 16, v113
	v_and_b32_e32 v113, 0xffff0000, v113
	v_pk_fma_f32 v[58:59], v[58:59], v[120:121], v[244:245] op_sel_hi:[1,0,1]
	v_pk_fma_f32 v[62:63], v[62:63], v[120:121], v[240:241] op_sel_hi:[1,0,1]
	v_mul_f32_e32 v58, 0xbfb8aa3b, v58
	v_mul_f32_e32 v62, 0xbfb8aa3b, v62
	v_pk_fma_f32 v[60:61], v[60:61], v[120:121], v[246:247] op_sel_hi:[1,0,1]
	v_exp_f32_e32 v128, v62
	v_exp_f32_e32 v62, v58
	v_mul_f32_e32 v58, 0xbfb8aa3b, v63
	v_pk_fma_f32 v[64:65], v[64:65], v[120:121], v[242:243] op_sel_hi:[1,0,1]
	v_exp_f32_e32 v129, v58
	v_mul_f32_e32 v58, 0xbfb8aa3b, v59
	v_mul_f32_e32 v59, 0xbfb8aa3b, v60
	v_exp_f32_e32 v63, v58
	v_mul_f32_e32 v58, 0xbfb8aa3b, v64
	v_exp_f32_e32 v60, v59
	v_mul_f32_e32 v59, 0xbfb8aa3b, v65
	v_exp_f32_e32 v58, v58
	v_exp_f32_e32 v59, v59
	v_pk_add_f32 v[62:63], v[62:63], 1.0 op_sel_hi:[1,0]
	v_mul_f32_e32 v61, 0xbfb8aa3b, v61
	v_exp_f32_e32 v61, v61
	v_pk_add_f32 v[64:65], v[58:59], 1.0 op_sel_hi:[1,0]
	v_pk_add_f32 v[58:59], v[128:129], 1.0 op_sel_hi:[1,0]
	v_pk_add_f32 v[60:61], v[60:61], 1.0 op_sel_hi:[1,0]
	s_nop 0
	v_rcp_f32_e32 v128, v59
	s_nop 0
	v_fma_f32 v131, -v59, v128, 1.0
	v_fma_f32 v59, v131, v128, v128
	s_nop 0
	v_rcp_f32_e32 v128, v58
	s_nop 0
	v_fma_f32 v131, -v58, v128, 1.0
	v_fma_f32 v58, v131, v128, v128
	v_pk_fma_f32 v[58:59], v[58:59], v[124:125], v[106:107]
	v_rcp_f32_e32 v128, v65
	s_nop 0
	v_fma_f32 v131, -v65, v128, 1.0
	v_fma_f32 v65, v131, v128, v128
	s_nop 0
	v_rcp_f32_e32 v128, v64
	s_nop 0
	v_fma_f32 v131, -v64, v128, 1.0
	v_fma_f32 v64, v131, v128, v128
	s_nop 0
	v_rcp_f32_e32 v128, v63
	s_nop 0
	v_fma_f32 v131, -v63, v128, 1.0
	v_fma_f32 v63, v131, v128, v128
	s_nop 0
	v_rcp_f32_e32 v128, v62
	s_nop 0
	v_fma_f32 v131, -v62, v128, 1.0
	v_fma_f32 v62, v131, v128, v128
	v_pk_fma_f32 v[62:63], v[62:63], v[110:111], v[94:95]
	v_rcp_f32_e32 v128, v61
	s_nop 0
	v_fma_f32 v131, -v61, v128, 1.0
	v_fma_f32 v129, v131, v128, v128
	s_nop 0
	v_rcp_f32_e32 v61, v60
	s_nop 0
	v_fma_f32 v131, -v60, v61, 1.0
	v_fma_f32 v128, v131, v61, v61
	v_pk_fma_f32 v[60:61], v[64:65], v[126:127], v[108:109]
	v_pk_fma_f32 v[64:65], v[128:129], v[112:113], v[96:97]
	global_store_dwordx4 v[122:123], v[58:61], off
	global_store_dwordx4 v[122:123], v[62:65], off offset:16
	s_nop 0
	s_nop 0
	v_mul_f32_e32 v62, v62, v62
	v_fmac_f32_e32 v62, v58, v58
	v_mul_f32_e32 v58, v63, v63
	v_fmac_f32_e32 v58, v59, v59
	v_add_f32_e32 v58, v62, v58
	v_mul_f32_e32 v59, v64, v64
	v_lshlrev_b32_e32 v62, 16, v90
	v_and_b32_e32 v63, 0xffff0000, v90
	v_fmac_f32_e32 v59, v60, v60
	v_add_f32_e32 v58, v59, v58
	v_mul_f32_e32 v59, v65, v65
	v_lshlrev_b32_e32 v64, 16, v91
	v_and_b32_e32 v65, 0xffff0000, v91
	v_fmac_f32_e32 v59, v61, v61
	v_add_f32_e32 v94, v59, v58
	v_lshlrev_b32_e32 v58, 16, v92
	v_and_b32_e32 v59, 0xffff0000, v92
	v_lshlrev_b32_e32 v60, 16, v93
	v_and_b32_e32 v61, 0xffff0000, v93
	v_pk_fma_f32 v[50:51], v[50:51], v[120:121], v[232:233] op_sel_hi:[1,0,1]
	v_pk_fma_f32 v[54:55], v[54:55], v[120:121], v[248:249] op_sel_hi:[1,0,1]
	v_mul_f32_e32 v50, 0xbfb8aa3b, v50
	v_pk_fma_f32 v[52:53], v[52:53], v[120:121], v[234:235] op_sel_hi:[1,0,1]
	v_exp_f32_e32 v90, v50
	v_mul_f32_e32 v50, 0xbfb8aa3b, v55
	v_pk_fma_f32 v[56:57], v[56:57], v[120:121], v[250:251] op_sel_hi:[1,0,1]
	v_exp_f32_e32 v55, v50
	v_mul_f32_e32 v50, 0xbfb8aa3b, v51
	v_mul_f32_e32 v51, 0xbfb8aa3b, v52
	v_mul_f32_e32 v54, 0xbfb8aa3b, v54
	v_exp_f32_e32 v91, v50
	v_mul_f32_e32 v50, 0xbfb8aa3b, v56
	v_exp_f32_e32 v52, v51
	v_mul_f32_e32 v51, 0xbfb8aa3b, v57
	v_exp_f32_e32 v54, v54
	v_exp_f32_e32 v50, v50
	v_exp_f32_e32 v51, v51
	v_mul_f32_e32 v53, 0xbfb8aa3b, v53
	v_exp_f32_e32 v53, v53
	v_pk_add_f32 v[56:57], v[50:51], 1.0 op_sel_hi:[1,0]
	v_pk_add_f32 v[50:51], v[54:55], 1.0 op_sel_hi:[1,0]
	v_pk_add_f32 v[52:53], v[52:53], 1.0 op_sel_hi:[1,0]
	s_nop 0
	v_rcp_f32_e32 v54, v51
	s_nop 0
	v_fma_f32 v93, -v51, v54, 1.0
	v_fma_f32 v51, v93, v54, v54
	s_nop 0
	v_rcp_f32_e32 v54, v50
	s_nop 0
	v_fma_f32 v93, -v50, v54, 1.0
	v_fma_f32 v50, v93, v54, v54
	v_pk_fma_f32 v[50:51], v[50:51], v[62:63], v[86:87]
	v_rcp_f32_e32 v54, v57
	s_nop 0
	v_fma_f32 v93, -v57, v54, 1.0
	v_fma_f32 v55, v93, v54, v54
	s_nop 0
	v_rcp_f32_e32 v93, v56
	s_nop 0
	v_fma_f32 v95, -v56, v93, 1.0
	v_fma_f32 v54, v95, v93, v93
	v_pk_add_f32 v[56:57], v[90:91], 1.0 op_sel_hi:[1,0]
	s_nop 0
	s_nop 0
	v_rcp_f32_e32 v90, v57
	s_nop 0
	v_fma_f32 v93, -v57, v90, 1.0
	v_fma_f32 v91, v93, v90, v90
	s_nop 0
	v_rcp_f32_e32 v57, v56
	s_nop 0
	v_fma_f32 v93, -v56, v57, 1.0
	v_fma_f32 v90, v93, v57, v57
	s_nop 0
	v_rcp_f32_e32 v56, v53
	s_nop 0
	v_fma_f32 v93, -v53, v56, 1.0
	v_fma_f32 v57, v93, v56, v56
	s_nop 0
	v_rcp_f32_e32 v53, v52
	s_nop 0
	v_fma_f32 v93, -v52, v53, 1.0
	v_fma_f32 v56, v93, v53, v53
	v_pk_fma_f32 v[52:53], v[54:55], v[64:65], v[88:89]
	v_pk_fma_f32 v[54:55], v[90:91], v[58:59], v[82:83]
	v_pk_fma_f32 v[56:57], v[56:57], v[60:61], v[84:85]
	global_store_dwordx4 v[122:123], v[50:53], off offset:512
	global_store_dwordx4 v[122:123], v[54:57], off offset:528
	s_nop 1
	v_mul_f32_e32 v54, v54, v54
	v_fmac_f32_e32 v54, v50, v50
	v_add_f32_e32 v50, v94, v54
	v_mul_f32_e32 v54, v55, v55
	v_fmac_f32_e32 v54, v51, v51
	v_mul_f32_e32 v51, v56, v56
	v_add_f32_e32 v50, v54, v50
	v_fmac_f32_e32 v51, v52, v52
	v_add_f32_e32 v50, v51, v50
	v_mul_f32_e32 v51, v57, v57
	v_fmac_f32_e32 v51, v53, v53
	v_add_f32_e32 v50, v51, v50
	ds_bpermute_b32 v51, v225, v50
	s_waitcnt lgkmcnt(0)
	v_add_f32_e32 v50, v50, v51
	ds_bpermute_b32 v51, v226, v50
	s_and_saveexec_b64 s[2:3], s[42:43]
	s_cbranch_execz .LBB0_791
	v_lshl_add_u64 v[52:53], v[114:115], 2, s[36:37]
	s_waitcnt lgkmcnt(0)
	v_add_f32_e32 v50, v50, v51
	global_atomic_add_f32 v[52:53], v50, off
; #define NTL(p) __builtin_nontemporal_load((const f32x4*)(p))
; #define NTS(v, p) __builtin_nontemporal_store((v), (f32x4*)(p))
; __device__ __forceinline__ float bf_lo(unsigned w) { return __uint_as_float(w << 16); }
; __device__ __forceinline__ float bf_hi(unsigned w) { return __uint_as_float(w & 0xffff0000u); }
; __device__ __forceinline__ float sigmoidf_(float x) { return 1.0f / (1.0f + __expf(-x)); }
;     __device__ __forceinline__ void operator()(AccT& acc, const Unit& u, int wr, int wc, int fr, int fq) const {
;     ...
;         for (int r = 0; r < 8; ++r) { const int ai = r >> 2, m = r & 3; const int row = row0 + ai * 128 + m * 16;
;             if (r < 7) { const int rn = row0 + ((r + 1) >> 2) * 128 + ((r + 1) & 3) * 16; const float* hn = H + (size_t)rn * DM + col0; const bf16_t* pn = ppbase + (((r + 1) >> 2) * 128 + ((r + 1) & 3) * 16) * 256;
;                 hv[(r + 1) & 1][0] = NTL(hn); hv[(r + 1) & 1][1] = NTL(hn + 4); hv[(r + 1) & 1][2] = NTL(hn + 128); hv[(r + 1) & 1][3] = NTL(hn + 132);
;                 pv[(r + 1) & 1][0] = *(const u32x4*)pn; pv[(r + 1) & 1][1] = *(const u32x4*)(pn + 128); rs[(r + 1) & 1] = rss2[rn]; }
;             float* hp = H + (size_t)row * DM + col0; float ss = 0.f; const float rstd = rsqrtf(rs[r & 1] * (1.0f / DM) + 1e-6f);
; #pragma unroll
;             for (int bj = 0; bj < 2; ++bj) { const u32x4 pw = pv[r & 1][bj];
;                 const f32x4 b0 = *(const f32x4*)(bias + col0 + bj * 128), b1 = *(const f32x4*)(bias + col0 + bj * 128 + 4);
;                 const f32x4 p0 = (f32x4){bf_lo(pw.x), bf_hi(pw.x), bf_lo(pw.y), bf_hi(pw.y)}, p1 = (f32x4){bf_lo(pw.z), bf_hi(pw.z), bf_lo(pw.w), bf_hi(pw.w)};
;                 f32x4 g0 = acc[ai][bj][m][0] * rstd + b0, g1 = acc[ai][bj][m][1] * rstd + b1;
; #pragma unroll
;                 for (int j = 0; j < 4; ++j) { g0[j] = sigmoidf_(g0[j]); g1[j] = sigmoidf_(g1[j]); }
;                 const f32x4 v0 = hv[r & 1][2 * bj] + p0 * g0, v1 = hv[r & 1][2 * bj + 1] + p1 * g1;
;                 NTS(v0, hp + bj * 128); NTS(v1, hp + bj * 128 + 4);
; #pragma unroll
;                 for (int j = 0; j < 4; ++j) ss += v0[j] * v0[j] + v1[j] * v1[j]; }
;             ss += __shfl_xor(ss, 16); ss += __shfl_xor(ss, 32);
;             if (fq == 0) unsafeAtomicAdd(rss3 + row, ss); __builtin_amdgcn_sched_barrier(0); }
.LBB0_791:
	s_or_b64 exec, exec, s[2:3]
	v_add_u32_e32 v90, 0xa0, v186
	v_ashrrev_i32_e32 v91, 31, v90
	s_waitcnt lgkmcnt(0)
	v_lshlrev_b64 v[50:51], 12, v[90:91]
	v_lshl_add_u64 v[50:51], s[22:23], 0, v[50:51]
	v_add_co_u32_e32 v58, vcc, 0x14000, v190
	v_lshl_add_u64 v[92:93], v[192:193], 2, v[50:51]
	s_nop 0
	v_addc_co_u32_e32 v59, vcc, 0, v191, vcc
	global_load_dwordx4 v[62:65], v[92:93], off offset:16 nt
	global_load_dwordx4 v[82:85], v[92:93], off nt
	global_load_dwordx4 v[50:53], v[92:93], off offset:528 nt
	global_load_dwordx4 v[54:57], v[92:93], off offset:512 nt
	global_load_dwordx4 v[86:89], v[58:59], off
	s_nop 0
	global_load_dwordx4 v[58:61], v[58:59], off offset:256
	s_nop 0
	global_load_dword v95, v[188:189], off offset:640
	s_waitcnt vmcnt(11)
	v_fmamk_f32 v94, v121, 0x3a800000, v210
	v_cmp_gt_f32_e32 vcc, s30, v94
	v_mul_f32_e32 v96, 0x4b800000, v94
	v_and_b32_e32 v97, 0xffff0000, v104
	v_cndmask_b32_e32 v94, v94, v96, vcc
	v_rsq_f32_e32 v94, v94
	v_lshlrev_b32_e32 v106, 16, v102
	v_and_b32_e32 v107, 0xffff0000, v102
	v_lshlrev_b32_e32 v108, 16, v103
	v_mul_f32_e32 v96, 0x45800000, v94
	v_cndmask_b32_e32 v94, v94, v96, vcc
	v_lshlrev_b32_e32 v96, 16, v104
	v_and_b32_e32 v109, 0xffff0000, v103
	v_lshlrev_b32_e32 v102, 16, v105
	v_and_b32_e32 v103, 0xffff0000, v105
	v_pk_fma_f32 v[42:43], v[42:43], v[94:95], v[244:245] op_sel_hi:[1,0,1]
	v_pk_fma_f32 v[46:47], v[46:47], v[94:95], v[240:241] op_sel_hi:[1,0,1]
	v_mul_f32_e32 v42, 0xbfb8aa3b, v42
	v_mul_f32_e32 v46, 0xbfb8aa3b, v46
	v_pk_fma_f32 v[44:45], v[44:45], v[94:95], v[246:247] op_sel_hi:[1,0,1]
	v_exp_f32_e32 v104, v46
	v_exp_f32_e32 v46, v42
	v_mul_f32_e32 v42, 0xbfb8aa3b, v47
	v_pk_fma_f32 v[48:49], v[48:49], v[94:95], v[242:243] op_sel_hi:[1,0,1]
	v_exp_f32_e32 v105, v42
	v_mul_f32_e32 v42, 0xbfb8aa3b, v43
	v_mul_f32_e32 v43, 0xbfb8aa3b, v44
	v_exp_f32_e32 v47, v42
	v_mul_f32_e32 v42, 0xbfb8aa3b, v48
	v_exp_f32_e32 v44, v43
	v_mul_f32_e32 v43, 0xbfb8aa3b, v49
	v_exp_f32_e32 v42, v42
	v_exp_f32_e32 v43, v43
	v_pk_add_f32 v[46:47], v[46:47], 1.0 op_sel_hi:[1,0]
	v_mul_f32_e32 v45, 0xbfb8aa3b, v45
	v_exp_f32_e32 v45, v45
	v_pk_add_f32 v[48:49], v[42:43], 1.0 op_sel_hi:[1,0]
	v_pk_add_f32 v[42:43], v[104:105], 1.0 op_sel_hi:[1,0]
	v_pk_add_f32 v[44:45], v[44:45], 1.0 op_sel_hi:[1,0]
	s_nop 0
	v_rcp_f32_e32 v104, v43
	s_nop 0
	v_fma_f32 v111, -v43, v104, 1.0
	v_fma_f32 v43, v111, v104, v104
	s_nop 0
	v_rcp_f32_e32 v104, v42
	s_nop 0
	v_fma_f32 v111, -v42, v104, 1.0
	v_fma_f32 v42, v111, v104, v104
	v_pk_fma_f32 v[42:43], v[42:43], v[106:107], v[98:99]
	v_rcp_f32_e32 v104, v49
	s_nop 0
	v_fma_f32 v111, -v49, v104, 1.0
	v_fma_f32 v49, v111, v104, v104
	s_nop 0
	v_rcp_f32_e32 v104, v48
	s_nop 0
	v_fma_f32 v111, -v48, v104, 1.0
	v_fma_f32 v48, v111, v104, v104
	s_nop 0
	v_rcp_f32_e32 v104, v47
	s_nop 0
	v_fma_f32 v111, -v47, v104, 1.0
	v_fma_f32 v47, v111, v104, v104
	s_nop 0
	v_rcp_f32_e32 v104, v46
	s_nop 0
	v_fma_f32 v111, -v46, v104, 1.0
	v_fma_f32 v46, v111, v104, v104
	v_pk_fma_f32 v[46:47], v[46:47], v[96:97], v[78:79]
	v_rcp_f32_e32 v104, v45
	s_nop 0
	v_fma_f32 v111, -v45, v104, 1.0
	v_fma_f32 v105, v111, v104, v104
	s_nop 0
	v_rcp_f32_e32 v45, v44
	s_nop 0
	v_fma_f32 v111, -v44, v45, 1.0
	v_fma_f32 v104, v111, v45, v45
	v_pk_fma_f32 v[44:45], v[48:49], v[108:109], v[100:101]
	v_pk_fma_f32 v[48:49], v[104:105], v[102:103], v[80:81]
	global_store_dwordx4 v[118:119], v[42:45], off
	global_store_dwordx4 v[118:119], v[46:49], off offset:16
	s_nop 0
	s_nop 0
	v_mul_f32_e32 v46, v46, v46
	v_fmac_f32_e32 v46, v42, v42
	v_mul_f32_e32 v42, v47, v47
	v_fmac_f32_e32 v42, v43, v43
	v_add_f32_e32 v42, v46, v42
	v_mul_f32_e32 v43, v48, v48
	v_lshlrev_b32_e32 v46, 16, v74
	v_and_b32_e32 v47, 0xffff0000, v74
	v_fmac_f32_e32 v43, v44, v44
	v_add_f32_e32 v42, v43, v42
	v_mul_f32_e32 v43, v49, v49
	v_lshlrev_b32_e32 v48, 16, v75
	v_and_b32_e32 v49, 0xffff0000, v75
	v_fmac_f32_e32 v43, v45, v45
	v_add_f32_e32 v78, v43, v42
	v_lshlrev_b32_e32 v42, 16, v76
	v_and_b32_e32 v43, 0xffff0000, v76
	v_lshlrev_b32_e32 v44, 16, v77
	v_and_b32_e32 v45, 0xffff0000, v77
	v_pk_fma_f32 v[34:35], v[34:35], v[94:95], v[232:233] op_sel_hi:[1,0,1]
	v_pk_fma_f32 v[38:39], v[38:39], v[94:95], v[248:249] op_sel_hi:[1,0,1]
	v_mul_f32_e32 v34, 0xbfb8aa3b, v34
	v_pk_fma_f32 v[36:37], v[36:37], v[94:95], v[234:235] op_sel_hi:[1,0,1]
	v_exp_f32_e32 v74, v34
	v_mul_f32_e32 v34, 0xbfb8aa3b, v39
	v_pk_fma_f32 v[40:41], v[40:41], v[94:95], v[250:251] op_sel_hi:[1,0,1]
	v_exp_f32_e32 v39, v34
	v_mul_f32_e32 v34, 0xbfb8aa3b, v35
	v_mul_f32_e32 v35, 0xbfb8aa3b, v36
	v_mul_f32_e32 v38, 0xbfb8aa3b, v38
	v_exp_f32_e32 v75, v34
	v_mul_f32_e32 v34, 0xbfb8aa3b, v40
	v_exp_f32_e32 v36, v35
	v_mul_f32_e32 v35, 0xbfb8aa3b, v41
	v_exp_f32_e32 v38, v38
	v_exp_f32_e32 v34, v34
	v_exp_f32_e32 v35, v35
	v_mul_f32_e32 v37, 0xbfb8aa3b, v37
	v_exp_f32_e32 v37, v37
	v_pk_add_f32 v[40:41], v[34:35], 1.0 op_sel_hi:[1,0]
	v_pk_add_f32 v[34:35], v[38:39], 1.0 op_sel_hi:[1,0]
	v_pk_add_f32 v[36:37], v[36:37], 1.0 op_sel_hi:[1,0]
	s_nop 0
	v_rcp_f32_e32 v38, v35
	s_nop 0
	v_fma_f32 v77, -v35, v38, 1.0
	v_fma_f32 v35, v77, v38, v38
	s_nop 0
	v_rcp_f32_e32 v38, v34
	s_nop 0
	v_fma_f32 v77, -v34, v38, 1.0
	v_fma_f32 v34, v77, v38, v38
	v_pk_fma_f32 v[34:35], v[34:35], v[46:47], v[70:71]
	v_rcp_f32_e32 v38, v41
	s_nop 0
	v_fma_f32 v77, -v41, v38, 1.0
	v_fma_f32 v39, v77, v38, v38
	s_nop 0
	v_rcp_f32_e32 v77, v40
	s_nop 0
	v_fma_f32 v79, -v40, v77, 1.0
	v_fma_f32 v38, v79, v77, v77
	v_pk_add_f32 v[40:41], v[74:75], 1.0 op_sel_hi:[1,0]
	s_nop 0
	s_nop 0
	v_rcp_f32_e32 v74, v41
	s_nop 0
	v_fma_f32 v77, -v41, v74, 1.0
	v_fma_f32 v75, v77, v74, v74
	s_nop 0
	v_rcp_f32_e32 v41, v40
	s_nop 0
	v_fma_f32 v77, -v40, v41, 1.0
	v_fma_f32 v74, v77, v41, v41
	s_nop 0
	v_rcp_f32_e32 v40, v37
	s_nop 0
	v_fma_f32 v77, -v37, v40, 1.0
	v_fma_f32 v41, v77, v40, v40
	s_nop 0
	v_rcp_f32_e32 v37, v36
	s_nop 0
	v_fma_f32 v77, -v36, v37, 1.0
	v_fma_f32 v40, v77, v37, v37
	v_pk_fma_f32 v[36:37], v[38:39], v[48:49], v[72:73]
	v_pk_fma_f32 v[38:39], v[74:75], v[42:43], v[66:67]
	v_pk_fma_f32 v[40:41], v[40:41], v[44:45], v[68:69]
	global_store_dwordx4 v[118:119], v[34:37], off offset:512
	global_store_dwordx4 v[118:119], v[38:41], off offset:528
	s_nop 1
	v_mul_f32_e32 v38, v38, v38
	v_fmac_f32_e32 v38, v34, v34
	v_add_f32_e32 v34, v78, v38
	v_mul_f32_e32 v38, v39, v39
	v_fmac_f32_e32 v38, v35, v35
	v_mul_f32_e32 v35, v40, v40
	v_add_f32_e32 v34, v38, v34
	v_fmac_f32_e32 v35, v36, v36
	v_add_f32_e32 v34, v35, v34
	v_mul_f32_e32 v35, v41, v41
	v_fmac_f32_e32 v35, v37, v37
	v_add_f32_e32 v34, v35, v34
	ds_bpermute_b32 v35, v225, v34
	s_waitcnt lgkmcnt(0)
	v_add_f32_e32 v34, v34, v35
	ds_bpermute_b32 v35, v226, v34
	s_and_saveexec_b64 s[2:3], s[42:43]
	s_cbranch_execz .LBB0_793
	v_lshl_add_u64 v[36:37], v[116:117], 2, s[36:37]
	s_waitcnt lgkmcnt(0)
	v_add_f32_e32 v34, v34, v35
	global_atomic_add_f32 v[36:37], v34, off
; #define NTL(p) __builtin_nontemporal_load((const f32x4*)(p))
; #define NTS(v, p) __builtin_nontemporal_store((v), (f32x4*)(p))
; __device__ __forceinline__ float bf_lo(unsigned w) { return __uint_as_float(w << 16); }
; __device__ __forceinline__ float bf_hi(unsigned w) { return __uint_as_float(w & 0xffff0000u); }
; __device__ __forceinline__ float sigmoidf_(float x) { return 1.0f / (1.0f + __expf(-x)); }
;     __device__ __forceinline__ void operator()(AccT& acc, const Unit& u, int wr, int wc, int fr, int fq) const {
;     ...
;         for (int r = 0; r < 8; ++r) { const int ai = r >> 2, m = r & 3; const int row = row0 + ai * 128 + m * 16;
;             if (r < 7) { const int rn = row0 + ((r + 1) >> 2) * 128 + ((r + 1) & 3) * 16; const float* hn = H + (size_t)rn * DM + col0; const bf16_t* pn = ppbase + (((r + 1) >> 2) * 128 + ((r + 1) & 3) * 16) * 256;
;                 hv[(r + 1) & 1][0] = NTL(hn); hv[(r + 1) & 1][1] = NTL(hn + 4); hv[(r + 1) & 1][2] = NTL(hn + 128); hv[(r + 1) & 1][3] = NTL(hn + 132);
;                 pv[(r + 1) & 1][0] = *(const u32x4*)pn; pv[(r + 1) & 1][1] = *(const u32x4*)(pn + 128); rs[(r + 1) & 1] = rss2[rn]; }
;             float* hp = H + (size_t)row * DM + col0; float ss = 0.f; const float rstd = rsqrtf(rs[r & 1] * (1.0f / DM) + 1e-6f);
; #pragma unroll
;             for (int bj = 0; bj < 2; ++bj) { const u32x4 pw = pv[r & 1][bj];
;                 const f32x4 b0 = *(const f32x4*)(bias + col0 + bj * 128), b1 = *(const f32x4*)(bias + col0 + bj * 128 + 4);
;                 const f32x4 p0 = (f32x4){bf_lo(pw.x), bf_hi(pw.x), bf_lo(pw.y), bf_hi(pw.y)}, p1 = (f32x4){bf_lo(pw.z), bf_hi(pw.z), bf_lo(pw.w), bf_hi(pw.w)};
;                 f32x4 g0 = acc[ai][bj][m][0] * rstd + b0, g1 = acc[ai][bj][m][1] * rstd + b1;
; #pragma unroll
;                 for (int j = 0; j < 4; ++j) { g0[j] = sigmoidf_(g0[j]); g1[j] = sigmoidf_(g1[j]); }
;                 const f32x4 v0 = hv[r & 1][2 * bj] + p0 * g0, v1 = hv[r & 1][2 * bj + 1] + p1 * g1;
;                 NTS(v0, hp + bj * 128); NTS(v1, hp + bj * 128 + 4);
; #pragma unroll
;                 for (int j = 0; j < 4; ++j) ss += v0[j] * v0[j] + v1[j] * v1[j]; }
;             ss += __shfl_xor(ss, 16); ss += __shfl_xor(ss, 32);
;             if (fq == 0) unsafeAtomicAdd(rss3 + row, ss); __builtin_amdgcn_sched_barrier(0); }
.LBB0_793:
	s_or_b64 exec, exec, s[2:3]
	v_add_u32_e32 v74, 0xb0, v186
	v_ashrrev_i32_e32 v75, 31, v74
	s_waitcnt lgkmcnt(0)
	v_lshlrev_b64 v[34:35], 12, v[74:75]
	v_lshl_add_u64 v[34:35], s[22:23], 0, v[34:35]
	v_add_co_u32_e32 v42, vcc, 0x16000, v190
	v_lshl_add_u64 v[76:77], v[192:193], 2, v[34:35]
	s_nop 0
	v_addc_co_u32_e32 v43, vcc, 0, v191, vcc
	global_load_dwordx4 v[46:49], v[76:77], off offset:16 nt
	global_load_dwordx4 v[66:69], v[76:77], off nt
	global_load_dwordx4 v[34:37], v[76:77], off offset:528 nt
	global_load_dwordx4 v[38:41], v[76:77], off offset:512 nt
	global_load_dwordx4 v[70:73], v[42:43], off
	s_nop 0
	global_load_dwordx4 v[42:45], v[42:43], off offset:256
	s_nop 0
	global_load_dword v79, v[188:189], off offset:704
	s_waitcnt vmcnt(11)
	v_fmamk_f32 v78, v95, 0x3a800000, v210
	v_cmp_gt_f32_e32 vcc, s30, v78
	v_mul_f32_e32 v80, 0x4b800000, v78
	v_and_b32_e32 v81, 0xffff0000, v88
	v_cndmask_b32_e32 v78, v78, v80, vcc
	v_rsq_f32_e32 v78, v78
	v_lshlrev_b32_e32 v94, 16, v86
	v_and_b32_e32 v95, 0xffff0000, v86
	v_lshlrev_b32_e32 v96, 16, v87
	v_mul_f32_e32 v80, 0x45800000, v78
	v_cndmask_b32_e32 v78, v78, v80, vcc
	v_lshlrev_b32_e32 v80, 16, v88
	v_and_b32_e32 v97, 0xffff0000, v87
	v_lshlrev_b32_e32 v86, 16, v89
	v_and_b32_e32 v87, 0xffff0000, v89
	v_pk_fma_f32 v[26:27], v[26:27], v[78:79], v[244:245] op_sel_hi:[1,0,1]
	v_pk_fma_f32 v[30:31], v[30:31], v[78:79], v[240:241] op_sel_hi:[1,0,1]
	v_mul_f32_e32 v26, 0xbfb8aa3b, v26
	v_mul_f32_e32 v30, 0xbfb8aa3b, v30
	v_pk_fma_f32 v[28:29], v[28:29], v[78:79], v[246:247] op_sel_hi:[1,0,1]
	v_exp_f32_e32 v88, v30
	v_exp_f32_e32 v30, v26
	v_mul_f32_e32 v26, 0xbfb8aa3b, v31
	v_pk_fma_f32 v[32:33], v[32:33], v[78:79], v[242:243] op_sel_hi:[1,0,1]
	v_exp_f32_e32 v89, v26
	v_mul_f32_e32 v26, 0xbfb8aa3b, v27
	v_mul_f32_e32 v27, 0xbfb8aa3b, v28
	v_exp_f32_e32 v31, v26
	v_mul_f32_e32 v26, 0xbfb8aa3b, v32
	v_exp_f32_e32 v28, v27
	v_mul_f32_e32 v27, 0xbfb8aa3b, v33
	v_exp_f32_e32 v26, v26
	v_exp_f32_e32 v27, v27
	v_pk_add_f32 v[30:31], v[30:31], 1.0 op_sel_hi:[1,0]
	v_mul_f32_e32 v29, 0xbfb8aa3b, v29
	v_exp_f32_e32 v29, v29
	v_pk_add_f32 v[32:33], v[26:27], 1.0 op_sel_hi:[1,0]
	v_pk_add_f32 v[26:27], v[88:89], 1.0 op_sel_hi:[1,0]
	v_pk_add_f32 v[28:29], v[28:29], 1.0 op_sel_hi:[1,0]
	s_nop 0
	v_rcp_f32_e32 v88, v27
	s_nop 0
	v_fma_f32 v99, -v27, v88, 1.0
	v_fma_f32 v27, v99, v88, v88
	s_nop 0
	v_rcp_f32_e32 v88, v26
	s_nop 0
	v_fma_f32 v99, -v26, v88, 1.0
	v_fma_f32 v26, v99, v88, v88
	v_pk_fma_f32 v[26:27], v[26:27], v[94:95], v[82:83]
	v_rcp_f32_e32 v88, v33
	s_nop 0
	v_fma_f32 v99, -v33, v88, 1.0
	v_fma_f32 v33, v99, v88, v88
	s_nop 0
	v_rcp_f32_e32 v88, v32
	s_nop 0
	v_fma_f32 v99, -v32, v88, 1.0
	v_fma_f32 v32, v99, v88, v88
	s_nop 0
	v_rcp_f32_e32 v88, v31
	s_nop 0
	v_fma_f32 v99, -v31, v88, 1.0
	v_fma_f32 v31, v99, v88, v88
	s_nop 0
	v_rcp_f32_e32 v88, v30
	s_nop 0
	v_fma_f32 v99, -v30, v88, 1.0
	v_fma_f32 v30, v99, v88, v88
	v_pk_fma_f32 v[30:31], v[30:31], v[80:81], v[62:63]
	v_rcp_f32_e32 v88, v29
	s_nop 0
	v_fma_f32 v99, -v29, v88, 1.0
	v_fma_f32 v89, v99, v88, v88
	s_nop 0
	v_rcp_f32_e32 v29, v28
	s_nop 0
	v_fma_f32 v99, -v28, v29, 1.0
	v_fma_f32 v88, v99, v29, v29
	v_pk_fma_f32 v[28:29], v[32:33], v[96:97], v[84:85]
	v_pk_fma_f32 v[32:33], v[88:89], v[86:87], v[64:65]
	global_store_dwordx4 v[92:93], v[26:29], off
	global_store_dwordx4 v[92:93], v[30:33], off offset:16
	s_nop 0
	s_nop 0
	v_mul_f32_e32 v30, v30, v30
	v_fmac_f32_e32 v30, v26, v26
	v_mul_f32_e32 v26, v31, v31
	v_fmac_f32_e32 v26, v27, v27
	v_add_f32_e32 v26, v30, v26
	v_mul_f32_e32 v27, v32, v32
	v_lshlrev_b32_e32 v30, 16, v58
	v_and_b32_e32 v31, 0xffff0000, v58
	v_fmac_f32_e32 v27, v28, v28
	v_add_f32_e32 v26, v27, v26
	v_mul_f32_e32 v27, v33, v33
	v_lshlrev_b32_e32 v32, 16, v59
	v_and_b32_e32 v33, 0xffff0000, v59
	v_fmac_f32_e32 v27, v29, v29
	v_add_f32_e32 v62, v27, v26
	v_lshlrev_b32_e32 v26, 16, v60
	v_and_b32_e32 v27, 0xffff0000, v60
	v_lshlrev_b32_e32 v28, 16, v61
	v_and_b32_e32 v29, 0xffff0000, v61
	v_pk_fma_f32 v[18:19], v[18:19], v[78:79], v[232:233] op_sel_hi:[1,0,1]
	v_pk_fma_f32 v[22:23], v[22:23], v[78:79], v[248:249] op_sel_hi:[1,0,1]
	v_mul_f32_e32 v18, 0xbfb8aa3b, v18
	v_pk_fma_f32 v[20:21], v[20:21], v[78:79], v[234:235] op_sel_hi:[1,0,1]
	v_exp_f32_e32 v58, v18
	v_mul_f32_e32 v18, 0xbfb8aa3b, v23
	v_pk_fma_f32 v[24:25], v[24:25], v[78:79], v[250:251] op_sel_hi:[1,0,1]
	v_exp_f32_e32 v23, v18
	v_mul_f32_e32 v18, 0xbfb8aa3b, v19
	v_mul_f32_e32 v19, 0xbfb8aa3b, v20
	v_mul_f32_e32 v22, 0xbfb8aa3b, v22
	v_exp_f32_e32 v59, v18
	v_mul_f32_e32 v18, 0xbfb8aa3b, v24
	v_exp_f32_e32 v20, v19
	v_mul_f32_e32 v19, 0xbfb8aa3b, v25
	v_exp_f32_e32 v22, v22
	v_exp_f32_e32 v18, v18
	v_exp_f32_e32 v19, v19
	v_mul_f32_e32 v21, 0xbfb8aa3b, v21
	v_exp_f32_e32 v21, v21
	v_pk_add_f32 v[24:25], v[18:19], 1.0 op_sel_hi:[1,0]
	v_pk_add_f32 v[18:19], v[22:23], 1.0 op_sel_hi:[1,0]
	v_pk_add_f32 v[20:21], v[20:21], 1.0 op_sel_hi:[1,0]
	s_nop 0
	v_rcp_f32_e32 v22, v19
	s_nop 0
	v_fma_f32 v61, -v19, v22, 1.0
	v_fma_f32 v19, v61, v22, v22
	s_nop 0
	v_rcp_f32_e32 v22, v18
	s_nop 0
	v_fma_f32 v61, -v18, v22, 1.0
	v_fma_f32 v18, v61, v22, v22
	v_pk_fma_f32 v[18:19], v[18:19], v[30:31], v[54:55]
	v_rcp_f32_e32 v22, v25
	s_nop 0
	v_fma_f32 v61, -v25, v22, 1.0
	v_fma_f32 v23, v61, v22, v22
	s_nop 0
	v_rcp_f32_e32 v61, v24
	s_nop 0
	v_fma_f32 v63, -v24, v61, 1.0
	v_fma_f32 v22, v63, v61, v61
	v_pk_add_f32 v[24:25], v[58:59], 1.0 op_sel_hi:[1,0]
	s_nop 0
	s_nop 0
	v_rcp_f32_e32 v58, v25
	s_nop 0
	v_fma_f32 v61, -v25, v58, 1.0
	v_fma_f32 v59, v61, v58, v58
	s_nop 0
	v_rcp_f32_e32 v25, v24
	s_nop 0
	v_fma_f32 v61, -v24, v25, 1.0
	v_fma_f32 v58, v61, v25, v25
	s_nop 0
	v_rcp_f32_e32 v24, v21
	s_nop 0
	v_fma_f32 v61, -v21, v24, 1.0
	v_fma_f32 v25, v61, v24, v24
	s_nop 0
	v_rcp_f32_e32 v21, v20
	s_nop 0
	v_fma_f32 v61, -v20, v21, 1.0
	v_fma_f32 v24, v61, v21, v21
	v_pk_fma_f32 v[20:21], v[22:23], v[32:33], v[56:57]
	v_pk_fma_f32 v[22:23], v[58:59], v[26:27], v[50:51]
	v_pk_fma_f32 v[24:25], v[24:25], v[28:29], v[52:53]
	global_store_dwordx4 v[92:93], v[18:21], off offset:512
	global_store_dwordx4 v[92:93], v[22:25], off offset:528
	s_nop 1
	v_mul_f32_e32 v22, v22, v22
	v_fmac_f32_e32 v22, v18, v18
	v_add_f32_e32 v18, v62, v22
	v_mul_f32_e32 v22, v23, v23
	v_fmac_f32_e32 v22, v19, v19
	v_mul_f32_e32 v19, v24, v24
	v_add_f32_e32 v18, v22, v18
	v_fmac_f32_e32 v19, v20, v20
	v_add_f32_e32 v18, v19, v18
	v_mul_f32_e32 v19, v25, v25
	v_fmac_f32_e32 v19, v21, v21
	v_add_f32_e32 v18, v19, v18
	ds_bpermute_b32 v19, v225, v18
	s_waitcnt lgkmcnt(0)
	v_add_f32_e32 v18, v18, v19
	ds_bpermute_b32 v19, v226, v18
	s_and_saveexec_b64 s[2:3], s[42:43]
	s_cbranch_execz .LBB0_795
	v_lshl_add_u64 v[20:21], v[90:91], 2, s[36:37]
	s_waitcnt lgkmcnt(0)
	v_add_f32_e32 v18, v18, v19
	global_atomic_add_f32 v[20:21], v18, off
; #define NTS(v, p) __builtin_nontemporal_store((v), (f32x4*)(p))
; __device__ __forceinline__ float bf_lo(unsigned w) { return __uint_as_float(w << 16); }
; __device__ __forceinline__ float bf_hi(unsigned w) { return __uint_as_float(w & 0xffff0000u); }
; __device__ __forceinline__ float sigmoidf_(float x) { return 1.0f / (1.0f + __expf(-x)); }
;     __device__ __forceinline__ void operator()(AccT& acc, const Unit& u, int wr, int wc, int fr, int fq) const {
;     ...
;             float* hp = H + (size_t)row * DM + col0; float ss = 0.f; const float rstd = rsqrtf(rs[r & 1] * (1.0f / DM) + 1e-6f);
; #pragma unroll
;             for (int bj = 0; bj < 2; ++bj) { const u32x4 pw = pv[r & 1][bj];
;                 const f32x4 b0 = *(const f32x4*)(bias + col0 + bj * 128), b1 = *(const f32x4*)(bias + col0 + bj * 128 + 4);
;                 const f32x4 p0 = (f32x4){bf_lo(pw.x), bf_hi(pw.x), bf_lo(pw.y), bf_hi(pw.y)}, p1 = (f32x4){bf_lo(pw.z), bf_hi(pw.z), bf_lo(pw.w), bf_hi(pw.w)};
;                 f32x4 g0 = acc[ai][bj][m][0] * rstd + b0, g1 = acc[ai][bj][m][1] * rstd + b1;
; #pragma unroll
;                 for (int j = 0; j < 4; ++j) { g0[j] = sigmoidf_(g0[j]); g1[j] = sigmoidf_(g1[j]); }
;                 const f32x4 v0 = hv[r & 1][2 * bj] + p0 * g0, v1 = hv[r & 1][2 * bj + 1] + p1 * g1;
;                 NTS(v0, hp + bj * 128); NTS(v1, hp + bj * 128 + 4);
; #pragma unroll
;                 for (int j = 0; j < 4; ++j) ss += v0[j] * v0[j] + v1[j] * v1[j]; }
;             ss += __shfl_xor(ss, 16); ss += __shfl_xor(ss, 32);
;             if (fq == 0) unsafeAtomicAdd(rss3 + row, ss); __builtin_amdgcn_sched_barrier(0); }
.LBB0_795:
	s_or_b64 exec, exec, s[2:3]
	s_waitcnt vmcnt(4)
	v_fmamk_f32 v18, v79, 0x3a800000, v210
	v_cmp_gt_f32_e32 vcc, s30, v18
	s_waitcnt lgkmcnt(0)
	v_mul_f32_e32 v19, 0x4b800000, v18
	v_lshlrev_b32_e32 v22, 16, v70
	v_cndmask_b32_e32 v18, v18, v19, vcc
	v_rsq_f32_e32 v18, v18
	v_and_b32_e32 v23, 0xffff0000, v70
	v_lshlrev_b32_e32 v24, 16, v71
	v_and_b32_e32 v25, 0xffff0000, v71
	v_mul_f32_e32 v19, 0x45800000, v18
	v_cndmask_b32_e32 v18, v18, v19, vcc
	v_lshlrev_b32_e32 v20, 16, v72
	v_and_b32_e32 v21, 0xffff0000, v72
	v_lshlrev_b32_e32 v26, 16, v73
	v_and_b32_e32 v27, 0xffff0000, v73
	v_pk_fma_f32 v[10:11], v[10:11], v[18:19], v[244:245] op_sel_hi:[1,0,1]
	v_pk_fma_f32 v[14:15], v[14:15], v[18:19], v[240:241] op_sel_hi:[1,0,1]
	v_mul_f32_e32 v10, 0xbfb8aa3b, v10
	v_pk_fma_f32 v[32:33], v[16:17], v[18:19], v[242:243] op_sel_hi:[1,0,1]
	v_pk_fma_f32 v[16:17], v[12:13], v[18:19], v[246:247] op_sel_hi:[1,0,1]
	v_mul_f32_e32 v12, 0xbfb8aa3b, v14
	v_exp_f32_e32 v14, v10
	v_mul_f32_e32 v10, 0xbfb8aa3b, v15
	v_exp_f32_e32 v13, v10
	v_mul_f32_e32 v10, 0xbfb8aa3b, v11
	v_mul_f32_e32 v11, 0xbfb8aa3b, v16
	v_exp_f32_e32 v15, v10
	v_mul_f32_e32 v10, 0xbfb8aa3b, v32
	v_exp_f32_e32 v16, v11
	v_mul_f32_e32 v11, 0xbfb8aa3b, v33
	v_exp_f32_e32 v12, v12
	v_exp_f32_e32 v10, v10
	v_exp_f32_e32 v11, v11
	v_pk_add_f32 v[14:15], v[14:15], 1.0 op_sel_hi:[1,0]
	v_mul_f32_e32 v17, 0xbfb8aa3b, v17
	v_exp_f32_e32 v17, v17
	v_pk_add_f32 v[28:29], v[10:11], 1.0 op_sel_hi:[1,0]
	v_pk_add_f32 v[10:11], v[12:13], 1.0 op_sel_hi:[1,0]
	v_pk_add_f32 v[16:17], v[16:17], 1.0 op_sel_hi:[1,0]
	s_nop 0
	v_rcp_f32_e32 v12, v11
	s_nop 0
	v_fma_f32 v30, -v11, v12, 1.0
	v_fma_f32 v11, v30, v12, v12
	s_nop 0
	v_rcp_f32_e32 v12, v10
	s_nop 0
	v_fma_f32 v30, -v10, v12, 1.0
	v_fma_f32 v10, v30, v12, v12
	v_pk_fma_f32 v[10:11], v[10:11], v[22:23], v[66:67]
	v_rcp_f32_e32 v12, v29
	s_nop 0
	v_fma_f32 v30, -v29, v12, 1.0
	v_fma_f32 v13, v30, v12, v12
	s_nop 0
	v_rcp_f32_e32 v30, v28
	s_nop 0
	v_fma_f32 v31, -v28, v30, 1.0
	v_fma_f32 v12, v31, v30, v30
	v_pk_fma_f32 v[12:13], v[12:13], v[24:25], v[68:69]
	v_rcp_f32_e32 v19, v15
	s_nop 0
	v_fma_f32 v30, -v15, v19, 1.0
	v_fma_f32 v15, v30, v19, v19
	s_nop 0
	v_rcp_f32_e32 v19, v14
	s_nop 0
	v_fma_f32 v30, -v14, v19, 1.0
	v_fma_f32 v14, v30, v19, v19
	v_pk_fma_f32 v[14:15], v[14:15], v[20:21], v[46:47]
	v_rcp_f32_e32 v19, v17
	s_nop 0
	v_fma_f32 v30, -v17, v19, 1.0
	v_fma_f32 v17, v30, v19, v19
	s_nop 0
	v_rcp_f32_e32 v19, v16
	s_nop 0
	v_fma_f32 v30, -v16, v19, 1.0
	v_fma_f32 v16, v30, v19, v19
	v_pk_fma_f32 v[16:17], v[16:17], v[26:27], v[48:49]
	global_store_dwordx4 v[76:77], v[10:13], off
	global_store_dwordx4 v[76:77], v[14:17], off offset:16
	s_nop 0
	s_nop 0
	v_mul_f32_e32 v14, v14, v14
	v_fmac_f32_e32 v14, v10, v10
	v_mul_f32_e32 v10, v15, v15
	v_fmac_f32_e32 v10, v11, v11
	v_mul_f32_e32 v11, v16, v16
	v_add_f32_e32 v10, v14, v10
	v_fmac_f32_e32 v11, v12, v12
	v_add_f32_e32 v10, v11, v10
	v_mul_f32_e32 v11, v17, v17
	v_fmac_f32_e32 v11, v13, v13
	v_add_f32_e32 v19, v11, v10
	v_lshlrev_b32_e32 v14, 16, v42
	v_and_b32_e32 v15, 0xffff0000, v42
	v_lshlrev_b32_e32 v16, 16, v43
	v_and_b32_e32 v17, 0xffff0000, v43
	v_lshlrev_b32_e32 v10, 16, v44
	v_and_b32_e32 v11, 0xffff0000, v44
	v_lshlrev_b32_e32 v12, 16, v45
	v_and_b32_e32 v13, 0xffff0000, v45
	v_pk_fma_f32 v[2:3], v[2:3], v[18:19], v[232:233] op_sel_hi:[1,0,1]
	v_pk_fma_f32 v[6:7], v[6:7], v[18:19], v[248:249] op_sel_hi:[1,0,1]
	v_mul_f32_e32 v2, 0xbfb8aa3b, v2
	v_pk_fma_f32 v[4:5], v[4:5], v[18:19], v[234:235] op_sel_hi:[1,0,1]
	v_exp_f32_e32 v20, v2
	v_mul_f32_e32 v2, 0xbfb8aa3b, v7
	v_pk_fma_f32 v[8:9], v[8:9], v[18:19], v[250:251] op_sel_hi:[1,0,1]
	v_exp_f32_e32 v7, v2
	v_mul_f32_e32 v2, 0xbfb8aa3b, v3
	v_mul_f32_e32 v3, 0xbfb8aa3b, v4
	v_mul_f32_e32 v6, 0xbfb8aa3b, v6
	v_exp_f32_e32 v21, v2
	v_mul_f32_e32 v2, 0xbfb8aa3b, v8
	v_exp_f32_e32 v4, v3
	v_mul_f32_e32 v3, 0xbfb8aa3b, v9
	v_exp_f32_e32 v6, v6
	v_exp_f32_e32 v2, v2
	v_exp_f32_e32 v3, v3
	v_mul_f32_e32 v5, 0xbfb8aa3b, v5
	v_exp_f32_e32 v5, v5
	v_pk_add_f32 v[8:9], v[2:3], 1.0 op_sel_hi:[1,0]
	v_pk_add_f32 v[2:3], v[6:7], 1.0 op_sel_hi:[1,0]
	v_pk_add_f32 v[4:5], v[4:5], 1.0 op_sel_hi:[1,0]
	s_nop 0
	v_rcp_f32_e32 v6, v3
	s_nop 0
	v_fma_f32 v22, -v3, v6, 1.0
	v_fma_f32 v3, v22, v6, v6
	s_nop 0
	v_rcp_f32_e32 v6, v2
	s_nop 0
	v_fma_f32 v22, -v2, v6, 1.0
	v_fma_f32 v2, v22, v6, v6
	v_pk_fma_f32 v[2:3], v[2:3], v[14:15], v[38:39]
	v_rcp_f32_e32 v6, v9
	s_nop 0
	v_fma_f32 v22, -v9, v6, 1.0
	v_fma_f32 v7, v22, v6, v6
	s_nop 0
	v_rcp_f32_e32 v22, v8
	s_nop 0
	v_fma_f32 v23, -v8, v22, 1.0
	v_fma_f32 v6, v23, v22, v22
	v_pk_add_f32 v[8:9], v[20:21], 1.0 op_sel_hi:[1,0]
	s_nop 0
	s_nop 0
	v_rcp_f32_e32 v18, v9
	s_nop 0
	v_fma_f32 v22, -v9, v18, 1.0
	v_fma_f32 v21, v22, v18, v18
	s_nop 0
	v_rcp_f32_e32 v9, v8
	s_nop 0
	v_fma_f32 v22, -v8, v9, 1.0
	v_fma_f32 v20, v22, v9, v9
	s_nop 0
	v_rcp_f32_e32 v8, v5
	s_nop 0
	v_fma_f32 v22, -v5, v8, 1.0
	v_fma_f32 v9, v22, v8, v8
	s_nop 0
	v_rcp_f32_e32 v5, v4
	s_nop 0
	v_fma_f32 v22, -v4, v5, 1.0
	v_fma_f32 v8, v22, v5, v5
	v_pk_fma_f32 v[4:5], v[6:7], v[16:17], v[40:41]
	v_pk_fma_f32 v[6:7], v[20:21], v[10:11], v[34:35]
	v_pk_fma_f32 v[8:9], v[8:9], v[12:13], v[36:37]
	global_store_dwordx4 v[76:77], v[2:5], off offset:512
	global_store_dwordx4 v[76:77], v[6:9], off offset:528
	s_nop 1
	v_mul_f32_e32 v6, v6, v6
	v_fmac_f32_e32 v6, v2, v2
	v_add_f32_e32 v2, v19, v6
	v_mul_f32_e32 v6, v7, v7
	v_fmac_f32_e32 v6, v3, v3
	v_mul_f32_e32 v3, v8, v8
	v_add_f32_e32 v2, v6, v2
	v_fmac_f32_e32 v3, v4, v4
	v_add_f32_e32 v2, v3, v2
	v_mul_f32_e32 v3, v9, v9
	v_fmac_f32_e32 v3, v5, v5
	v_add_f32_e32 v2, v3, v2
	ds_bpermute_b32 v3, v225, v2
	s_waitcnt lgkmcnt(0)
	v_add_f32_e32 v2, v2, v3
	ds_bpermute_b32 v3, v226, v2
	s_and_saveexec_b64 s[2:3], s[42:43]
	s_cbranch_execz .LBB0_766
	v_lshl_add_u64 v[4:5], v[74:75], 2, s[36:37]
	s_waitcnt lgkmcnt(0)
	v_add_f32_e32 v2, v2, v3
	global_atomic_add_f32 v[4:5], v2, off
	s_branch .LBB0_766
